# GEMM K-loops: wave priority inverted (load segments at priority 1, MFMA segments at 0)
# baseline (speedup 1.0000x reference)
; #define PG8_STAGE(bufoff, gbase, voff) do { _Pragma("unroll") for (int _i = 0; _i < 2; ++_i) \
;         __builtin_amdgcn_global_load_lds((const unsigned*)((const char*)(gbase) + (voff)[_i]), (PG8_LAS unsigned*)(lds + (bufoff) + ldsw + _i * 8192), 16, 0, 0); } while (0)
; #define PG8_LDA(dst, b, h) do { _Pragma("unroll") for (int m = 0; m < 4; ++m) _Pragma("unroll") for (int k = 0; k < 2; ++k) dst[m][k] = *(const PG8_LAS bf16x8*)(lds + PG8_SA(b, h) + aoff + m * 2048 + k * 1024); } while (0)
; #define PG8_LDB(dst, b, h) do { _Pragma("unroll") for (int n = 0; n < 2; ++n) _Pragma("unroll") for (int k = 0; k < 2; ++k) dst[n][k] = *(const PG8_LAS bf16x8*)(lds + PG8_SB(b, h) + boff + n * 2048 + k * 1024); } while (0)
; #define PG8_MMA(ai, bj, At, Bt) do { __builtin_amdgcn_s_setprio(1); _Pragma("unroll") for (int m = 0; m < 4; ++m) _Pragma("unroll") for (int n = 0; n < 2; ++n) _Pragma("unroll") for (int k = 0; k < 2; ++k) \
;         acc[ai][bj][m][n] = __builtin_amdgcn_mfma_f32_16x16x32_bf16(Bt[n][k], At[m][k], acc[ai][bj][m][n], 0, 0, 0); __builtin_amdgcn_s_setprio(0); } while (0)
; #define PG8_WAIT_V(n) asm volatile("s_waitcnt vmcnt(" #n ")" ::: "memory")
; #define PG8_WAIT_L(n) asm volatile("s_waitcnt lgkmcnt(" #n ")" ::: "memory")
; #define PG8_BAR __builtin_amdgcn_s_barrier()
; #define PG8_SCHED __builtin_amdgcn_sched_barrier(0)
; template <class Epi, class Sched, bool ALIGN_EPI = false, bool SP2 = false>
; __device__ __forceinline__ void gemm_phase(PG8_LAS unsigned char* lds, const Gemm g, const Sched& S, const Epi& E) {
;     ...
;             PG8_LDB(B0, 0, 0); PG8_LDB(B1, 0, 1); PG8_SCHED; PG8_LDA(At, 0, 0); PG8_STAGE(PG8_SA(1, 1), a1 + hstep, voffA);
;             PG8_WAIT_V(8); PG8_WAIT_L(0); PG8_BAR; PG8_MMA(0, 0, At, B0); PG8_MMA(0, 1, At, B1); PG8_BAR; PG8_SCHED;
;             PG8_LDA(At, 0, 1); PG8_STAGE(PG8_SB(0, 0), b2, voffB); PG8_STAGE(PG8_SB(0, 1), b2 + hstep, voffB); PG8_STAGE(PG8_SA(0, 0), a2, voffA);
;             PG8_WAIT_V(8); PG8_WAIT_L(0); PG8_BAR; PG8_MMA(1, 0, At, B0); PG8_MMA(1, 1, At, B1); PG8_BAR; PG8_SCHED;
.LBB0_213:
	s_or_b32 s21, s13, 1
	s_mul_i32 s46, s35, s21
	s_mul_hi_u32 s47, s34, s21
	s_add_i32 s47, s47, s46
	s_mul_i32 s21, s34, s21
	s_add_u32 s21, s30, s21
	s_addc_u32 s59, s31, s47
	s_add_u32 s46, s44, s42
	s_addc_u32 s47, s45, s43
	s_add_i32 s66, 0, 0x10000
	v_add_u32_e32 v150, s66, v159
	s_add_i32 s76, 0, 0x14000
	ds_read_b128 v[142:145], v150
	ds_read_b128 v[146:149], v150 offset:1024
	ds_read_b128 v[162:165], v150 offset:2048
	ds_read_b128 v[166:169], v150 offset:3072
	v_add_u32_e32 v150, s76, v159
	ds_read_b128 v[170:173], v150
	ds_read_b128 v[174:177], v150 offset:1024
	ds_read_b128 v[178:181], v150 offset:2048
	ds_read_b128 v[182:185], v150 offset:3072
	s_add_u32 s68, s21, 0x40000
	s_addc_u32 s69, s59, 0
	v_lshl_add_u64 v[150:151], s[68:69], 0, v[128:129]
	s_add_i32 m0, s29, 0xc000
	ds_read_b128 v[186:189], v161
	ds_read_b128 v[190:193], v161 offset:1024
	ds_read_b128 v[198:201], v161 offset:2048
	ds_read_b128 v[202:205], v161 offset:3072
	ds_read_b128 v[206:209], v161 offset:4096
	ds_read_b128 v[210:213], v161 offset:5120
	ds_read_b128 v[214:217], v161 offset:6144
	ds_read_b128 v[218:221], v161 offset:7168
	global_load_lds_dwordx4 v[150:151], off
	v_lshl_add_u64 v[150:151], s[68:69], 0, v[132:133]
	s_add_i32 m0, s29, 0xe000
	s_nop 0
	global_load_lds_dwordx4 v[150:151], off
	s_waitcnt vmcnt(8)
	s_waitcnt lgkmcnt(0)
	s_barrier
	s_setprio 0
	s_waitcnt lgkmcnt(0)
	v_mfma_f32_16x16x32_bf16 v[124:127], v[142:145], v[186:189], v[124:127]
	v_mfma_f32_16x16x32_bf16 v[120:123], v[162:165], v[186:189], v[120:123]
	v_mfma_f32_16x16x32_bf16 v[108:111], v[142:145], v[198:201], v[108:111]
	v_mfma_f32_16x16x32_bf16 v[104:107], v[162:165], v[198:201], v[104:107]
	v_mfma_f32_16x16x32_bf16 v[92:95], v[142:145], v[206:209], v[92:95]
	v_mfma_f32_16x16x32_bf16 v[88:91], v[162:165], v[206:209], v[88:91]
	v_mfma_f32_16x16x32_bf16 v[76:79], v[142:145], v[214:217], v[76:79]
	v_mfma_f32_16x16x32_bf16 v[72:75], v[162:165], v[214:217], v[72:75]
	v_mfma_f32_16x16x32_bf16 v[124:127], v[146:149], v[190:193], v[124:127]
	v_mfma_f32_16x16x32_bf16 v[120:123], v[166:169], v[190:193], v[120:123]
	v_mfma_f32_16x16x32_bf16 v[108:111], v[146:149], v[202:205], v[108:111]
	v_mfma_f32_16x16x32_bf16 v[104:107], v[166:169], v[202:205], v[104:107]
	v_mfma_f32_16x16x32_bf16 v[92:95], v[146:149], v[210:213], v[92:95]
	v_mfma_f32_16x16x32_bf16 v[88:91], v[166:169], v[210:213], v[88:91]
	v_mfma_f32_16x16x32_bf16 v[76:79], v[146:149], v[218:221], v[76:79]
	v_mfma_f32_16x16x32_bf16 v[72:75], v[166:169], v[218:221], v[72:75]
	s_setprio 1
	s_setprio 0
	v_mfma_f32_16x16x32_bf16 v[116:119], v[170:173], v[186:189], v[116:119]
	v_mfma_f32_16x16x32_bf16 v[112:115], v[178:181], v[186:189], v[112:115]
	v_mfma_f32_16x16x32_bf16 v[100:103], v[170:173], v[198:201], v[100:103]
	v_mfma_f32_16x16x32_bf16 v[96:99], v[178:181], v[198:201], v[96:99]
	v_mfma_f32_16x16x32_bf16 v[84:87], v[170:173], v[206:209], v[84:87]
	v_mfma_f32_16x16x32_bf16 v[80:83], v[178:181], v[206:209], v[80:83]
	v_mfma_f32_16x16x32_bf16 v[68:71], v[170:173], v[214:217], v[68:71]
	v_mfma_f32_16x16x32_bf16 v[64:67], v[178:181], v[214:217], v[64:67]
	v_mfma_f32_16x16x32_bf16 v[116:119], v[174:177], v[190:193], v[116:119]
	v_mfma_f32_16x16x32_bf16 v[112:115], v[182:185], v[190:193], v[112:115]
	v_mfma_f32_16x16x32_bf16 v[100:103], v[174:177], v[202:205], v[100:103]
	v_mfma_f32_16x16x32_bf16 v[96:99], v[182:185], v[202:205], v[96:99]
	v_mfma_f32_16x16x32_bf16 v[84:87], v[174:177], v[210:213], v[84:87]
	v_mfma_f32_16x16x32_bf16 v[80:83], v[182:185], v[210:213], v[80:83]
	v_mfma_f32_16x16x32_bf16 v[68:71], v[174:177], v[218:221], v[68:71]
	v_mfma_f32_16x16x32_bf16 v[64:67], v[182:185], v[218:221], v[64:67]
	s_setprio 1
	s_barrier
	s_add_i32 s21, s66, s50
	v_lshl_add_u64 v[150:151], s[40:41], 0, v[130:131]
	s_mov_b32 m0, s21
	ds_read_b128 v[186:189], v161 offset:16384
	ds_read_b128 v[190:193], v161 offset:17408
	ds_read_b128 v[198:201], v161 offset:18432
	ds_read_b128 v[202:205], v161 offset:19456
	ds_read_b128 v[206:209], v161 offset:20480
	ds_read_b128 v[210:213], v161 offset:21504
	ds_read_b128 v[214:217], v161 offset:22528
	ds_read_b128 v[218:221], v161 offset:23552
	global_load_lds_dwordx4 v[150:151], off
	s_add_i32 m0, s21, 0x2000
	s_add_u32 s68, s40, 0x40000
	v_lshl_add_u64 v[150:151], s[40:41], 0, v[134:135]
	s_addc_u32 s69, s41, 0
	s_add_i32 s21, s76, s50
	global_load_lds_dwordx4 v[150:151], off
	v_lshl_add_u64 v[150:151], s[68:69], 0, v[130:131]
	s_mov_b32 m0, s21
	s_nop 0
	global_load_lds_dwordx4 v[150:151], off
	v_lshl_add_u64 v[150:151], s[68:69], 0, v[134:135]
	s_add_i32 m0, s21, 0x2000
	s_nop 0
	global_load_lds_dwordx4 v[150:151], off
	v_lshl_add_u64 v[150:151], s[44:45], 0, v[128:129]
	s_mov_b32 m0, s29
	s_nop 0
	global_load_lds_dwordx4 v[150:151], off
	v_lshl_add_u64 v[150:151], s[44:45], 0, v[132:133]
	s_mov_b32 m0, s51
	s_nop 0
	global_load_lds_dwordx4 v[150:151], off
	s_waitcnt vmcnt(8)
	s_waitcnt lgkmcnt(0)
	s_barrier
; #define PG8_STAGE(bufoff, gbase, voff) do { _Pragma("unroll") for (int _i = 0; _i < 2; ++_i) \
;         __builtin_amdgcn_global_load_lds((const unsigned*)((const char*)(gbase) + (voff)[_i]), (PG8_LAS unsigned*)(lds + (bufoff) + ldsw + _i * 8192), 16, 0, 0); } while (0)
; #define PG8_LDA(dst, b, h) do { _Pragma("unroll") for (int m = 0; m < 4; ++m) _Pragma("unroll") for (int k = 0; k < 2; ++k) dst[m][k] = *(const PG8_LAS bf16x8*)(lds + PG8_SA(b, h) + aoff + m * 2048 + k * 1024); } while (0)
; #define PG8_LDB(dst, b, h) do { _Pragma("unroll") for (int n = 0; n < 2; ++n) _Pragma("unroll") for (int k = 0; k < 2; ++k) dst[n][k] = *(const PG8_LAS bf16x8*)(lds + PG8_SB(b, h) + boff + n * 2048 + k * 1024); } while (0)
; #define PG8_MMA(ai, bj, At, Bt) do { __builtin_amdgcn_s_setprio(1); _Pragma("unroll") for (int m = 0; m < 4; ++m) _Pragma("unroll") for (int n = 0; n < 2; ++n) _Pragma("unroll") for (int k = 0; k < 2; ++k) \
;         acc[ai][bj][m][n] = __builtin_amdgcn_mfma_f32_16x16x32_bf16(Bt[n][k], At[m][k], acc[ai][bj][m][n], 0, 0, 0); __builtin_amdgcn_s_setprio(0); } while (0)
; #define PG8_WAIT_V(n) asm volatile("s_waitcnt vmcnt(" #n ")" ::: "memory")
; #define PG8_WAIT_L(n) asm volatile("s_waitcnt lgkmcnt(" #n ")" ::: "memory")
; #define PG8_BAR __builtin_amdgcn_s_barrier()
; #define PG8_SCHED __builtin_amdgcn_sched_barrier(0)
; template <class Epi, class Sched, bool ALIGN_EPI = false, bool SP2 = false>
; __device__ __forceinline__ void gemm_phase(PG8_LAS unsigned char* lds, const Gemm g, const Sched& S, const Epi& E) {
;     ...
;             PG8_WAIT_V(8); PG8_WAIT_L(0); PG8_BAR; PG8_MMA(1, 0, At, B0); PG8_MMA(1, 1, At, B1); PG8_BAR; PG8_SCHED;
;             PG8_LDB(B0, 1, 0); PG8_LDB(B1, 1, 1); PG8_SCHED; PG8_LDA(At, 1, 0); PG8_STAGE(PG8_SA(0, 1), a2 + hstep, voffA);
;             PG8_WAIT_V(8); PG8_WAIT_L(0); PG8_BAR; PG8_MMA(0, 0, At, B0); PG8_MMA(0, 1, At, B1); PG8_BAR; PG8_SCHED;
	s_setprio 0
	s_waitcnt lgkmcnt(0)
	v_mfma_f32_16x16x32_bf16 v[60:63], v[142:145], v[186:189], v[60:63]
	v_mfma_f32_16x16x32_bf16 v[56:59], v[162:165], v[186:189], v[56:59]
	v_mfma_f32_16x16x32_bf16 v[44:47], v[142:145], v[198:201], v[44:47]
	v_mfma_f32_16x16x32_bf16 v[40:43], v[162:165], v[198:201], v[40:43]
	v_mfma_f32_16x16x32_bf16 v[28:31], v[142:145], v[206:209], v[28:31]
	v_mfma_f32_16x16x32_bf16 v[24:27], v[162:165], v[206:209], v[24:27]
	v_mfma_f32_16x16x32_bf16 v[12:15], v[142:145], v[214:217], v[12:15]
	v_mfma_f32_16x16x32_bf16 v[8:11], v[162:165], v[214:217], v[8:11]
	v_mfma_f32_16x16x32_bf16 v[60:63], v[146:149], v[190:193], v[60:63]
	v_mfma_f32_16x16x32_bf16 v[56:59], v[166:169], v[190:193], v[56:59]
	v_mfma_f32_16x16x32_bf16 v[44:47], v[146:149], v[202:205], v[44:47]
	v_mfma_f32_16x16x32_bf16 v[40:43], v[166:169], v[202:205], v[40:43]
	v_mfma_f32_16x16x32_bf16 v[28:31], v[146:149], v[210:213], v[28:31]
	v_mfma_f32_16x16x32_bf16 v[24:27], v[166:169], v[210:213], v[24:27]
	v_mfma_f32_16x16x32_bf16 v[12:15], v[146:149], v[218:221], v[12:15]
	v_mfma_f32_16x16x32_bf16 v[8:11], v[166:169], v[218:221], v[8:11]
	s_setprio 1
	s_setprio 0
	v_mfma_f32_16x16x32_bf16 v[52:55], v[170:173], v[186:189], v[52:55]
	v_mfma_f32_16x16x32_bf16 v[48:51], v[178:181], v[186:189], v[48:51]
	v_mfma_f32_16x16x32_bf16 v[36:39], v[170:173], v[198:201], v[36:39]
	v_mfma_f32_16x16x32_bf16 v[32:35], v[178:181], v[198:201], v[32:35]
	v_mfma_f32_16x16x32_bf16 v[20:23], v[170:173], v[206:209], v[20:23]
	v_mfma_f32_16x16x32_bf16 v[16:19], v[178:181], v[206:209], v[16:19]
	v_mfma_f32_16x16x32_bf16 v[4:7], v[170:173], v[214:217], v[4:7]
	v_mfma_f32_16x16x32_bf16 v[0:3], v[178:181], v[214:217], v[0:3]
	v_mfma_f32_16x16x32_bf16 v[52:55], v[174:177], v[190:193], v[52:55]
	v_mfma_f32_16x16x32_bf16 v[48:51], v[182:185], v[190:193], v[48:51]
	v_mfma_f32_16x16x32_bf16 v[36:39], v[174:177], v[202:205], v[36:39]
	v_mfma_f32_16x16x32_bf16 v[32:35], v[182:185], v[202:205], v[32:35]
	v_mfma_f32_16x16x32_bf16 v[20:23], v[174:177], v[210:213], v[20:23]
	v_mfma_f32_16x16x32_bf16 v[16:19], v[182:185], v[210:213], v[16:19]
	v_mfma_f32_16x16x32_bf16 v[4:7], v[174:177], v[218:221], v[4:7]
	v_mfma_f32_16x16x32_bf16 v[0:3], v[182:185], v[218:221], v[0:3]
	s_setprio 1
	s_barrier
	s_add_i32 s21, 0, 0x18000
	v_add_u32_e32 v150, s21, v159
	s_add_i32 s59, 0, 0x1c000
	ds_read_b128 v[142:145], v150
	ds_read_b128 v[146:149], v150 offset:1024
	ds_read_b128 v[162:165], v150 offset:2048
	ds_read_b128 v[166:169], v150 offset:3072
	v_add_u32_e32 v150, s59, v159
	ds_read_b128 v[170:173], v150
	ds_read_b128 v[174:177], v150 offset:1024
	ds_read_b128 v[178:181], v150 offset:2048
	ds_read_b128 v[182:185], v150 offset:3072
	s_add_u32 s44, s44, 0x40000
	s_addc_u32 s45, s45, 0
	s_mov_b32 m0, s52
	v_lshl_add_u64 v[150:151], s[44:45], 0, v[128:129]
	ds_read_b128 v[186:189], v161 offset:32768
	ds_read_b128 v[190:193], v161 offset:33792
	ds_read_b128 v[198:201], v161 offset:34816
	ds_read_b128 v[202:205], v161 offset:35840
	ds_read_b128 v[206:209], v161 offset:36864
	ds_read_b128 v[210:213], v161 offset:37888
	ds_read_b128 v[214:217], v161 offset:38912
	ds_read_b128 v[218:221], v161 offset:39936
	global_load_lds_dwordx4 v[150:151], off
	v_lshl_add_u64 v[150:151], s[44:45], 0, v[132:133]
	s_mov_b32 m0, s53
	s_nop 0
	global_load_lds_dwordx4 v[150:151], off
	s_waitcnt vmcnt(8)
	s_waitcnt lgkmcnt(0)
	s_barrier
	s_setprio 0
	s_waitcnt lgkmcnt(0)
	v_mfma_f32_16x16x32_bf16 v[124:127], v[142:145], v[186:189], v[124:127]
	v_mfma_f32_16x16x32_bf16 v[120:123], v[162:165], v[186:189], v[120:123]
	v_mfma_f32_16x16x32_bf16 v[108:111], v[142:145], v[198:201], v[108:111]
	v_mfma_f32_16x16x32_bf16 v[104:107], v[162:165], v[198:201], v[104:107]
	v_mfma_f32_16x16x32_bf16 v[92:95], v[142:145], v[206:209], v[92:95]
	v_mfma_f32_16x16x32_bf16 v[88:91], v[162:165], v[206:209], v[88:91]
	v_mfma_f32_16x16x32_bf16 v[76:79], v[142:145], v[214:217], v[76:79]
	v_mfma_f32_16x16x32_bf16 v[72:75], v[162:165], v[214:217], v[72:75]
	v_mfma_f32_16x16x32_bf16 v[124:127], v[146:149], v[190:193], v[124:127]
	v_mfma_f32_16x16x32_bf16 v[120:123], v[166:169], v[190:193], v[120:123]
	v_mfma_f32_16x16x32_bf16 v[108:111], v[146:149], v[202:205], v[108:111]
	v_mfma_f32_16x16x32_bf16 v[104:107], v[166:169], v[202:205], v[104:107]
	v_mfma_f32_16x16x32_bf16 v[92:95], v[146:149], v[210:213], v[92:95]
	v_mfma_f32_16x16x32_bf16 v[88:91], v[166:169], v[210:213], v[88:91]
	v_mfma_f32_16x16x32_bf16 v[76:79], v[146:149], v[218:221], v[76:79]
	v_mfma_f32_16x16x32_bf16 v[72:75], v[166:169], v[218:221], v[72:75]
	s_setprio 1
	s_setprio 0
	v_mfma_f32_16x16x32_bf16 v[116:119], v[170:173], v[186:189], v[116:119]
	v_mfma_f32_16x16x32_bf16 v[112:115], v[178:181], v[186:189], v[112:115]
	v_mfma_f32_16x16x32_bf16 v[100:103], v[170:173], v[198:201], v[100:103]
	v_mfma_f32_16x16x32_bf16 v[96:99], v[178:181], v[198:201], v[96:99]
	v_mfma_f32_16x16x32_bf16 v[84:87], v[170:173], v[206:209], v[84:87]
	v_mfma_f32_16x16x32_bf16 v[80:83], v[178:181], v[206:209], v[80:83]
	v_mfma_f32_16x16x32_bf16 v[68:71], v[170:173], v[214:217], v[68:71]
	v_mfma_f32_16x16x32_bf16 v[64:67], v[178:181], v[214:217], v[64:67]
	v_mfma_f32_16x16x32_bf16 v[116:119], v[174:177], v[190:193], v[116:119]
	v_mfma_f32_16x16x32_bf16 v[112:115], v[182:185], v[190:193], v[112:115]
	v_mfma_f32_16x16x32_bf16 v[100:103], v[174:177], v[202:205], v[100:103]
	v_mfma_f32_16x16x32_bf16 v[96:99], v[182:185], v[202:205], v[96:99]
	v_mfma_f32_16x16x32_bf16 v[84:87], v[174:177], v[210:213], v[84:87]
	v_mfma_f32_16x16x32_bf16 v[80:83], v[182:185], v[210:213], v[80:83]
	v_mfma_f32_16x16x32_bf16 v[68:71], v[174:177], v[218:221], v[68:71]
	v_mfma_f32_16x16x32_bf16 v[64:67], v[182:185], v[218:221], v[64:67]
	s_setprio 1
	s_barrier
; #define PG8_STAGE(bufoff, gbase, voff) do { _Pragma("unroll") for (int _i = 0; _i < 2; ++_i) \
;         __builtin_amdgcn_global_load_lds((const unsigned*)((const char*)(gbase) + (voff)[_i]), (PG8_LAS unsigned*)(lds + (bufoff) + ldsw + _i * 8192), 16, 0, 0); } while (0)
; #define PG8_LDA(dst, b, h) do { _Pragma("unroll") for (int m = 0; m < 4; ++m) _Pragma("unroll") for (int k = 0; k < 2; ++k) dst[m][k] = *(const PG8_LAS bf16x8*)(lds + PG8_SA(b, h) + aoff + m * 2048 + k * 1024); } while (0)
; #define PG8_MMA(ai, bj, At, Bt) do { __builtin_amdgcn_s_setprio(1); _Pragma("unroll") for (int m = 0; m < 4; ++m) _Pragma("unroll") for (int n = 0; n < 2; ++n) _Pragma("unroll") for (int k = 0; k < 2; ++k) \
;         acc[ai][bj][m][n] = __builtin_amdgcn_mfma_f32_16x16x32_bf16(Bt[n][k], At[m][k], acc[ai][bj][m][n], 0, 0, 0); __builtin_amdgcn_s_setprio(0); } while (0)
; #define PG8_WAIT_V(n) asm volatile("s_waitcnt vmcnt(" #n ")" ::: "memory")
; #define PG8_WAIT_L(n) asm volatile("s_waitcnt lgkmcnt(" #n ")" ::: "memory")
; #define PG8_BAR __builtin_amdgcn_s_barrier()
; #define PG8_SCHED __builtin_amdgcn_sched_barrier(0)
; template <class Epi, class Sched, bool ALIGN_EPI = false, bool SP2 = false>
; __device__ __forceinline__ void gemm_phase(PG8_LAS unsigned char* lds, const Gemm g, const Sched& S, const Epi& E) {
;     ...
;             PG8_LDA(At, 1, 1); PG8_STAGE(PG8_SB(1, 0), b3, voffB); PG8_STAGE(PG8_SB(1, 1), b3 + hstep, voffB); PG8_STAGE(PG8_SA(1, 0), a3, voffA);
;             PG8_WAIT_V(8); PG8_WAIT_L(0); PG8_BAR; PG8_MMA(1, 0, At, B0); PG8_MMA(1, 1, At, B1); PG8_BAR; PG8_SCHED;
	s_add_u32 s40, s40, s42
	s_addc_u32 s41, s41, s43
	s_add_i32 s21, s21, s50
	v_lshl_add_u64 v[150:151], s[40:41], 0, v[130:131]
	s_mov_b32 m0, s21
	ds_read_b128 v[186:189], v161 offset:49152
	ds_read_b128 v[190:193], v161 offset:50176
	ds_read_b128 v[198:201], v161 offset:51200
	ds_read_b128 v[202:205], v161 offset:52224
	ds_read_b128 v[206:209], v161 offset:53248
	ds_read_b128 v[210:213], v161 offset:54272
	ds_read_b128 v[214:217], v161 offset:55296
	ds_read_b128 v[218:221], v161 offset:56320
	global_load_lds_dwordx4 v[150:151], off
	s_add_i32 m0, s21, 0x2000
	v_lshl_add_u64 v[150:151], s[40:41], 0, v[134:135]
	s_add_u32 s40, s40, 0x40000
	s_addc_u32 s41, s41, 0
	s_add_i32 s21, s59, s50
	global_load_lds_dwordx4 v[150:151], off
	v_lshl_add_u64 v[150:151], s[40:41], 0, v[130:131]
	s_mov_b32 m0, s21
	s_nop 0
	global_load_lds_dwordx4 v[150:151], off
	v_lshl_add_u64 v[150:151], s[40:41], 0, v[134:135]
	s_add_i32 m0, s21, 0x2000
	s_nop 0
	global_load_lds_dwordx4 v[150:151], off
	v_lshl_add_u64 v[150:151], s[46:47], 0, v[128:129]
	s_mov_b32 m0, s55
	s_nop 0
	global_load_lds_dwordx4 v[150:151], off
	v_lshl_add_u64 v[150:151], s[46:47], 0, v[132:133]
	s_mov_b32 m0, s56
	s_nop 0
	global_load_lds_dwordx4 v[150:151], off
	s_waitcnt vmcnt(8)
	s_waitcnt lgkmcnt(0)
	s_barrier
	s_setprio 0
	s_waitcnt lgkmcnt(0)
	v_mfma_f32_16x16x32_bf16 v[60:63], v[142:145], v[186:189], v[60:63]
	v_mfma_f32_16x16x32_bf16 v[56:59], v[162:165], v[186:189], v[56:59]
	v_mfma_f32_16x16x32_bf16 v[44:47], v[142:145], v[198:201], v[44:47]
	v_mfma_f32_16x16x32_bf16 v[40:43], v[162:165], v[198:201], v[40:43]
	v_mfma_f32_16x16x32_bf16 v[28:31], v[142:145], v[206:209], v[28:31]
	v_mfma_f32_16x16x32_bf16 v[24:27], v[162:165], v[206:209], v[24:27]
	v_mfma_f32_16x16x32_bf16 v[12:15], v[142:145], v[214:217], v[12:15]
	v_mfma_f32_16x16x32_bf16 v[8:11], v[162:165], v[214:217], v[8:11]
	v_mfma_f32_16x16x32_bf16 v[60:63], v[146:149], v[190:193], v[60:63]
	v_mfma_f32_16x16x32_bf16 v[56:59], v[166:169], v[190:193], v[56:59]
	v_mfma_f32_16x16x32_bf16 v[44:47], v[146:149], v[202:205], v[44:47]
	v_mfma_f32_16x16x32_bf16 v[40:43], v[166:169], v[202:205], v[40:43]
	v_mfma_f32_16x16x32_bf16 v[28:31], v[146:149], v[210:213], v[28:31]
	v_mfma_f32_16x16x32_bf16 v[24:27], v[166:169], v[210:213], v[24:27]
	v_mfma_f32_16x16x32_bf16 v[12:15], v[146:149], v[218:221], v[12:15]
	v_mfma_f32_16x16x32_bf16 v[8:11], v[166:169], v[218:221], v[8:11]
	s_setprio 1
	s_setprio 0
	v_mfma_f32_16x16x32_bf16 v[52:55], v[170:173], v[186:189], v[52:55]
	v_mfma_f32_16x16x32_bf16 v[48:51], v[178:181], v[186:189], v[48:51]
	v_mfma_f32_16x16x32_bf16 v[36:39], v[170:173], v[198:201], v[36:39]
	v_mfma_f32_16x16x32_bf16 v[32:35], v[178:181], v[198:201], v[32:35]
	v_mfma_f32_16x16x32_bf16 v[20:23], v[170:173], v[206:209], v[20:23]
	v_mfma_f32_16x16x32_bf16 v[16:19], v[178:181], v[206:209], v[16:19]
	v_mfma_f32_16x16x32_bf16 v[4:7], v[170:173], v[214:217], v[4:7]
	v_mfma_f32_16x16x32_bf16 v[0:3], v[178:181], v[214:217], v[0:3]
	v_mfma_f32_16x16x32_bf16 v[52:55], v[174:177], v[190:193], v[52:55]
	v_mfma_f32_16x16x32_bf16 v[48:51], v[182:185], v[190:193], v[48:51]
	v_mfma_f32_16x16x32_bf16 v[36:39], v[174:177], v[202:205], v[36:39]
	v_mfma_f32_16x16x32_bf16 v[32:35], v[182:185], v[202:205], v[32:35]
	v_mfma_f32_16x16x32_bf16 v[20:23], v[174:177], v[210:213], v[20:23]
	v_mfma_f32_16x16x32_bf16 v[16:19], v[182:185], v[210:213], v[16:19]
	v_mfma_f32_16x16x32_bf16 v[4:7], v[174:177], v[218:221], v[4:7]
	v_mfma_f32_16x16x32_bf16 v[0:3], v[182:185], v[218:221], v[0:3]
	s_setprio 1
	s_barrier
	s_cmp_gt_u32 s13, 13
	s_mov_b32 s13, s19
	s_cbranch_scc1 .LBB0_218

; #define PG8_STAGE(bufoff, gbase, voff) do { _Pragma("unroll") for (int _i = 0; _i < 2; ++_i) \
;         __builtin_amdgcn_global_load_lds((const unsigned*)((const char*)(gbase) + (voff)[_i]), (PG8_LAS unsigned*)(lds + (bufoff) + ldsw + _i * 8192), 16, 0, 0); } while (0)
; #define PG8_LDA(dst, b, h) do { _Pragma("unroll") for (int m = 0; m < 4; ++m) _Pragma("unroll") for (int k = 0; k < 2; ++k) dst[m][k] = *(const PG8_LAS bf16x8*)(lds + PG8_SA(b, h) + aoff + m * 2048 + k * 1024); } while (0)
; #define PG8_LDB(dst, b, h) do { _Pragma("unroll") for (int n = 0; n < 2; ++n) _Pragma("unroll") for (int k = 0; k < 2; ++k) dst[n][k] = *(const PG8_LAS bf16x8*)(lds + PG8_SB(b, h) + boff + n * 2048 + k * 1024); } while (0)
; #define PG8_MMA(ai, bj, At, Bt) do { __builtin_amdgcn_s_setprio(1); _Pragma("unroll") for (int m = 0; m < 4; ++m) _Pragma("unroll") for (int n = 0; n < 2; ++n) _Pragma("unroll") for (int k = 0; k < 2; ++k) \
;         acc[ai][bj][m][n] = __builtin_amdgcn_mfma_f32_16x16x32_bf16(Bt[n][k], At[m][k], acc[ai][bj][m][n], 0, 0, 0); __builtin_amdgcn_s_setprio(0); } while (0)
; #define PG8_WAIT_V(n) asm volatile("s_waitcnt vmcnt(" #n ")" ::: "memory")
; #define PG8_WAIT_L(n) asm volatile("s_waitcnt lgkmcnt(" #n ")" ::: "memory")
; #define PG8_BAR __builtin_amdgcn_s_barrier()
; #define PG8_SCHED __builtin_amdgcn_sched_barrier(0)
; template <class Epi, class Sched, bool ALIGN_EPI = false, bool SP2 = false>
; __device__ __forceinline__ void gemm_phase(PG8_LAS unsigned char* lds, const Gemm g, const Sched& S, const Epi& E) {
;     ...
;             PG8_LDB(B0, 0, 0); PG8_LDB(B1, 0, 1); PG8_SCHED; PG8_LDA(At, 0, 0); PG8_STAGE(PG8_SA(1, 1), a1 + hstep, voffA);
;             PG8_WAIT_V(8); PG8_WAIT_L(0); PG8_BAR; PG8_MMA(0, 0, At, B0); PG8_MMA(0, 1, At, B1); PG8_BAR; PG8_SCHED;
;             PG8_LDA(At, 0, 1); PG8_STAGE(PG8_SB(0, 0), b2, voffB); PG8_STAGE(PG8_SB(0, 1), b2 + hstep, voffB); PG8_STAGE(PG8_SA(0, 0), a2, voffA);
;             PG8_WAIT_V(8); PG8_WAIT_L(0); PG8_BAR; PG8_MMA(1, 0, At, B0); PG8_MMA(1, 1, At, B1); PG8_BAR; PG8_SCHED;
.LBB0_531:
	s_add_i32 s59, s59, 2
	s_add_u32 s48, s46, s44
	s_addc_u32 s49, s47, s45
	s_add_i32 s66, 0, 0x10000
	s_add_i32 s92, 0, 0x14000
	v_add_u32_e32 v144, s66, v185
	v_add_u32_e32 v178, s92, v185
	ds_read_b128 v[100:103], v144
	ds_read_b128 v[104:107], v144 offset:1024
	ds_read_b128 v[112:115], v144 offset:2048
	ds_read_b128 v[144:147], v144 offset:3072
	ds_read_b128 v[148:151], v178
	ds_read_b128 v[170:173], v178 offset:1024
	ds_read_b128 v[174:177], v178 offset:2048
	ds_read_b128 v[178:181], v178 offset:3072
	v_lshl_add_u64 v[182:183], v[92:93], 0, s[40:41]
	s_add_i32 m0, s55, 0xc000
	ds_read_b128 v[188:191], v187
	ds_read_b128 v[198:201], v187 offset:1024
	ds_read_b128 v[202:205], v187 offset:2048
	ds_read_b128 v[206:209], v187 offset:3072
	ds_read_b128 v[210:213], v187 offset:4096
	ds_read_b128 v[214:217], v187 offset:5120
	ds_read_b128 v[218:221], v187 offset:6144
	ds_read_b128 v[222:225], v187 offset:7168
	global_load_lds_dwordx4 v[182:183], off
	v_lshl_add_u64 v[182:183], v[94:95], 0, s[40:41]
	s_add_i32 m0, s55, 0xe000
	s_nop 0
	global_load_lds_dwordx4 v[182:183], off
	s_waitcnt vmcnt(8)
	s_waitcnt lgkmcnt(0)
	s_barrier
	s_setprio 0
	s_waitcnt lgkmcnt(0)
	v_mfma_f32_16x16x32_bf16 v[140:143], v[100:103], v[188:191], v[140:143]
	v_mfma_f32_16x16x32_bf16 v[136:139], v[112:115], v[188:191], v[136:139]
	v_mfma_f32_16x16x32_bf16 v[124:127], v[100:103], v[202:205], v[124:127]
	v_mfma_f32_16x16x32_bf16 v[120:123], v[112:115], v[202:205], v[120:123]
	v_mfma_f32_16x16x32_bf16 v[96:99], v[100:103], v[210:213], v[96:99]
	v_mfma_f32_16x16x32_bf16 v[88:91], v[112:115], v[210:213], v[88:91]
	v_mfma_f32_16x16x32_bf16 v[76:79], v[100:103], v[218:221], v[76:79]
	v_mfma_f32_16x16x32_bf16 v[72:75], v[112:115], v[218:221], v[72:75]
	v_mfma_f32_16x16x32_bf16 v[140:143], v[104:107], v[198:201], v[140:143]
	v_mfma_f32_16x16x32_bf16 v[136:139], v[144:147], v[198:201], v[136:139]
	v_mfma_f32_16x16x32_bf16 v[124:127], v[104:107], v[206:209], v[124:127]
	v_mfma_f32_16x16x32_bf16 v[120:123], v[144:147], v[206:209], v[120:123]
	v_mfma_f32_16x16x32_bf16 v[96:99], v[104:107], v[214:217], v[96:99]
	v_mfma_f32_16x16x32_bf16 v[88:91], v[144:147], v[214:217], v[88:91]
	v_mfma_f32_16x16x32_bf16 v[76:79], v[104:107], v[222:225], v[76:79]
	v_mfma_f32_16x16x32_bf16 v[72:75], v[144:147], v[222:225], v[72:75]
	s_setprio 1
	s_setprio 0
	v_mfma_f32_16x16x32_bf16 v[132:135], v[148:151], v[188:191], v[132:135]
	v_mfma_f32_16x16x32_bf16 v[128:131], v[174:177], v[188:191], v[128:131]
	v_mfma_f32_16x16x32_bf16 v[116:119], v[148:151], v[202:205], v[116:119]
	v_mfma_f32_16x16x32_bf16 v[108:111], v[174:177], v[202:205], v[108:111]
	v_mfma_f32_16x16x32_bf16 v[84:87], v[148:151], v[210:213], v[84:87]
	v_mfma_f32_16x16x32_bf16 v[80:83], v[174:177], v[210:213], v[80:83]
	v_mfma_f32_16x16x32_bf16 v[68:71], v[148:151], v[218:221], v[68:71]
	v_mfma_f32_16x16x32_bf16 v[64:67], v[174:177], v[218:221], v[64:67]
	v_mfma_f32_16x16x32_bf16 v[132:135], v[170:173], v[198:201], v[132:135]
	v_mfma_f32_16x16x32_bf16 v[128:131], v[178:181], v[198:201], v[128:131]
	v_mfma_f32_16x16x32_bf16 v[116:119], v[170:173], v[206:209], v[116:119]
	v_mfma_f32_16x16x32_bf16 v[108:111], v[178:181], v[206:209], v[108:111]
	v_mfma_f32_16x16x32_bf16 v[84:87], v[170:173], v[214:217], v[84:87]
	v_mfma_f32_16x16x32_bf16 v[80:83], v[178:181], v[214:217], v[80:83]
	v_mfma_f32_16x16x32_bf16 v[68:71], v[170:173], v[222:225], v[68:71]
	v_mfma_f32_16x16x32_bf16 v[64:67], v[178:181], v[222:225], v[64:67]
	s_setprio 1
	s_barrier
	s_add_i32 s66, s66, s52
	v_lshl_add_u64 v[182:183], s[42:43], 0, v[154:155]
	s_mov_b32 m0, s66
	ds_read_b128 v[188:191], v187 offset:16384
	ds_read_b128 v[198:201], v187 offset:17408
	ds_read_b128 v[202:205], v187 offset:18432
	ds_read_b128 v[206:209], v187 offset:19456
	ds_read_b128 v[210:213], v187 offset:20480
	ds_read_b128 v[214:217], v187 offset:21504
	ds_read_b128 v[218:221], v187 offset:22528
	ds_read_b128 v[222:225], v187 offset:23552
	global_load_lds_dwordx4 v[182:183], off
	s_add_i32 m0, s66, 0x2000
	s_add_u32 s76, s42, 0x40000
	v_lshl_add_u64 v[182:183], s[42:43], 0, v[164:165]
	s_addc_u32 s77, s43, 0
	s_add_i32 s66, s92, s52
	global_load_lds_dwordx4 v[182:183], off
	v_lshl_add_u64 v[182:183], s[76:77], 0, v[154:155]
	s_mov_b32 m0, s66
	s_nop 0
	global_load_lds_dwordx4 v[182:183], off
	v_lshl_add_u64 v[182:183], s[76:77], 0, v[164:165]
	s_add_i32 m0, s66, 0x2000
	s_nop 0
	global_load_lds_dwordx4 v[182:183], off
	v_lshl_add_u64 v[182:183], s[46:47], 0, v[160:161]
	s_mov_b32 m0, s55
	s_nop 0
	global_load_lds_dwordx4 v[182:183], off
	v_lshl_add_u64 v[182:183], s[46:47], 0, v[162:163]
	s_mov_b32 m0, s56
	s_nop 0
	global_load_lds_dwordx4 v[182:183], off
	s_waitcnt vmcnt(8)
	s_waitcnt lgkmcnt(0)
	s_barrier
; #define PG8_STAGE(bufoff, gbase, voff) do { _Pragma("unroll") for (int _i = 0; _i < 2; ++_i) \
;         __builtin_amdgcn_global_load_lds((const unsigned*)((const char*)(gbase) + (voff)[_i]), (PG8_LAS unsigned*)(lds + (bufoff) + ldsw + _i * 8192), 16, 0, 0); } while (0)
; #define PG8_LDA(dst, b, h) do { _Pragma("unroll") for (int m = 0; m < 4; ++m) _Pragma("unroll") for (int k = 0; k < 2; ++k) dst[m][k] = *(const PG8_LAS bf16x8*)(lds + PG8_SA(b, h) + aoff + m * 2048 + k * 1024); } while (0)
; #define PG8_LDB(dst, b, h) do { _Pragma("unroll") for (int n = 0; n < 2; ++n) _Pragma("unroll") for (int k = 0; k < 2; ++k) dst[n][k] = *(const PG8_LAS bf16x8*)(lds + PG8_SB(b, h) + boff + n * 2048 + k * 1024); } while (0)
; #define PG8_MMA(ai, bj, At, Bt) do { __builtin_amdgcn_s_setprio(1); _Pragma("unroll") for (int m = 0; m < 4; ++m) _Pragma("unroll") for (int n = 0; n < 2; ++n) _Pragma("unroll") for (int k = 0; k < 2; ++k) \
;         acc[ai][bj][m][n] = __builtin_amdgcn_mfma_f32_16x16x32_bf16(Bt[n][k], At[m][k], acc[ai][bj][m][n], 0, 0, 0); __builtin_amdgcn_s_setprio(0); } while (0)
; #define PG8_WAIT_V(n) asm volatile("s_waitcnt vmcnt(" #n ")" ::: "memory")
; template <class Epi, class Sched, bool ALIGN_EPI = false, bool SP2 = false>
; __device__ __forceinline__ void gemm_phase(PG8_LAS unsigned char* lds, const Gemm g, const Sched& S, const Epi& E) {
;     ...
;             PG8_LDB(B0, 0, 0); PG8_LDB(B1, 0, 1); PG8_SCHED; PG8_LDA(At, 0, 0); PG8_STAGE(PG8_SA(1, 1), a1 + hstep, voffA);
;             PG8_WAIT_V(8); PG8_WAIT_L(0); PG8_BAR; PG8_MMA(0, 0, At, B0); PG8_MMA(0, 1, At, B1); PG8_BAR; PG8_SCHED;
;             PG8_LDA(At, 0, 1); PG8_STAGE(PG8_SB(0, 0), b2, voffB); PG8_STAGE(PG8_SB(0, 1), b2 + hstep, voffB); PG8_STAGE(PG8_SA(0, 0), a2, voffA);
;             PG8_WAIT_V(8); PG8_WAIT_L(0); PG8_BAR; PG8_MMA(1, 0, At, B0); PG8_MMA(1, 1, At, B1); PG8_BAR; PG8_SCHED;
;             PG8_LDB(B0, 1, 0); PG8_LDB(B1, 1, 1); PG8_SCHED; PG8_LDA(At, 1, 0); PG8_STAGE(PG8_SA(0, 1), a2 + hstep, voffA);
;             PG8_WAIT_V(8); PG8_WAIT_L(0); PG8_BAR; PG8_MMA(0, 0, At, B0); PG8_MMA(0, 1, At, B1); PG8_BAR; PG8_SCHED;
;             PG8_LDA(At, 1, 1); PG8_STAGE(PG8_SB(1, 0), b3, voffB); PG8_STAGE(PG8_SB(1, 1), b3 + hstep, voffB); PG8_STAGE(PG8_SA(1, 0), a3, voffA);
;             PG8_WAIT_V(8); PG8_WAIT_L(0); PG8_BAR; PG8_MMA(1, 0, At, B0); PG8_MMA(1, 1, At, B1); PG8_BAR; PG8_SCHED;
	s_setprio 0
	s_waitcnt lgkmcnt(0)
	v_mfma_f32_16x16x32_bf16 v[60:63], v[100:103], v[188:191], v[60:63]
	v_mfma_f32_16x16x32_bf16 v[56:59], v[112:115], v[188:191], v[56:59]
	v_mfma_f32_16x16x32_bf16 v[44:47], v[100:103], v[202:205], v[44:47]
	v_mfma_f32_16x16x32_bf16 v[40:43], v[112:115], v[202:205], v[40:43]
	v_mfma_f32_16x16x32_bf16 v[28:31], v[100:103], v[210:213], v[28:31]
	v_mfma_f32_16x16x32_bf16 v[24:27], v[112:115], v[210:213], v[24:27]
	v_mfma_f32_16x16x32_bf16 v[12:15], v[100:103], v[218:221], v[12:15]
	v_mfma_f32_16x16x32_bf16 v[8:11], v[112:115], v[218:221], v[8:11]
	v_mfma_f32_16x16x32_bf16 v[60:63], v[104:107], v[198:201], v[60:63]
	v_mfma_f32_16x16x32_bf16 v[56:59], v[144:147], v[198:201], v[56:59]
	v_mfma_f32_16x16x32_bf16 v[44:47], v[104:107], v[206:209], v[44:47]
	v_mfma_f32_16x16x32_bf16 v[40:43], v[144:147], v[206:209], v[40:43]
	v_mfma_f32_16x16x32_bf16 v[28:31], v[104:107], v[214:217], v[28:31]
	v_mfma_f32_16x16x32_bf16 v[24:27], v[144:147], v[214:217], v[24:27]
	v_mfma_f32_16x16x32_bf16 v[12:15], v[104:107], v[222:225], v[12:15]
	v_mfma_f32_16x16x32_bf16 v[8:11], v[144:147], v[222:225], v[8:11]
	s_setprio 1
	s_setprio 0
	v_mfma_f32_16x16x32_bf16 v[52:55], v[148:151], v[188:191], v[52:55]
	v_mfma_f32_16x16x32_bf16 v[48:51], v[174:177], v[188:191], v[48:51]
	v_mfma_f32_16x16x32_bf16 v[36:39], v[148:151], v[202:205], v[36:39]
	v_mfma_f32_16x16x32_bf16 v[32:35], v[174:177], v[202:205], v[32:35]
	v_mfma_f32_16x16x32_bf16 v[20:23], v[148:151], v[210:213], v[20:23]
	v_mfma_f32_16x16x32_bf16 v[16:19], v[174:177], v[210:213], v[16:19]
	v_mfma_f32_16x16x32_bf16 v[4:7], v[148:151], v[218:221], v[4:7]
	v_mfma_f32_16x16x32_bf16 v[0:3], v[174:177], v[218:221], v[0:3]
	v_mfma_f32_16x16x32_bf16 v[52:55], v[170:173], v[198:201], v[52:55]
	v_mfma_f32_16x16x32_bf16 v[48:51], v[178:181], v[198:201], v[48:51]
	v_mfma_f32_16x16x32_bf16 v[36:39], v[170:173], v[206:209], v[36:39]
	v_mfma_f32_16x16x32_bf16 v[32:35], v[178:181], v[206:209], v[32:35]
	v_mfma_f32_16x16x32_bf16 v[20:23], v[170:173], v[214:217], v[20:23]
	v_mfma_f32_16x16x32_bf16 v[16:19], v[178:181], v[214:217], v[16:19]
	v_mfma_f32_16x16x32_bf16 v[4:7], v[170:173], v[222:225], v[4:7]
	v_mfma_f32_16x16x32_bf16 v[0:3], v[178:181], v[222:225], v[0:3]
	s_setprio 1
	s_barrier
	s_add_i32 s66, 0, 0x18000
	s_add_i32 s76, 0, 0x1c000
	v_add_u32_e32 v144, s66, v185
	v_add_u32_e32 v178, s76, v185
	ds_read_b128 v[100:103], v144
	ds_read_b128 v[104:107], v144 offset:1024
	ds_read_b128 v[112:115], v144 offset:2048
	ds_read_b128 v[144:147], v144 offset:3072
	ds_read_b128 v[148:151], v178
	ds_read_b128 v[170:173], v178 offset:1024
	ds_read_b128 v[174:177], v178 offset:2048
	ds_read_b128 v[178:181], v178 offset:3072
	s_add_u32 s46, s46, 0x40000
	s_addc_u32 s47, s47, 0
	s_mov_b32 m0, s57
	v_lshl_add_u64 v[182:183], s[46:47], 0, v[160:161]
	ds_read_b128 v[188:191], v187 offset:32768
	ds_read_b128 v[198:201], v187 offset:33792
	ds_read_b128 v[202:205], v187 offset:34816
	ds_read_b128 v[206:209], v187 offset:35840
	ds_read_b128 v[210:213], v187 offset:36864
	ds_read_b128 v[214:217], v187 offset:37888
	ds_read_b128 v[218:221], v187 offset:38912
	ds_read_b128 v[222:225], v187 offset:39936
	global_load_lds_dwordx4 v[182:183], off
	v_lshl_add_u64 v[182:183], s[46:47], 0, v[162:163]
	s_mov_b32 m0, s60
	s_nop 0
	global_load_lds_dwordx4 v[182:183], off
	s_waitcnt vmcnt(8)
	s_waitcnt lgkmcnt(0)
	s_barrier
	s_setprio 0
	s_waitcnt lgkmcnt(0)
	v_mfma_f32_16x16x32_bf16 v[140:143], v[100:103], v[188:191], v[140:143]
	v_mfma_f32_16x16x32_bf16 v[136:139], v[112:115], v[188:191], v[136:139]
	v_mfma_f32_16x16x32_bf16 v[124:127], v[100:103], v[202:205], v[124:127]
	v_mfma_f32_16x16x32_bf16 v[120:123], v[112:115], v[202:205], v[120:123]
	v_mfma_f32_16x16x32_bf16 v[96:99], v[100:103], v[210:213], v[96:99]
	v_mfma_f32_16x16x32_bf16 v[88:91], v[112:115], v[210:213], v[88:91]
	v_mfma_f32_16x16x32_bf16 v[76:79], v[100:103], v[218:221], v[76:79]
	v_mfma_f32_16x16x32_bf16 v[72:75], v[112:115], v[218:221], v[72:75]
	v_mfma_f32_16x16x32_bf16 v[140:143], v[104:107], v[198:201], v[140:143]
	v_mfma_f32_16x16x32_bf16 v[136:139], v[144:147], v[198:201], v[136:139]
	v_mfma_f32_16x16x32_bf16 v[124:127], v[104:107], v[206:209], v[124:127]
	v_mfma_f32_16x16x32_bf16 v[120:123], v[144:147], v[206:209], v[120:123]
	v_mfma_f32_16x16x32_bf16 v[96:99], v[104:107], v[214:217], v[96:99]
	v_mfma_f32_16x16x32_bf16 v[88:91], v[144:147], v[214:217], v[88:91]
	v_mfma_f32_16x16x32_bf16 v[76:79], v[104:107], v[222:225], v[76:79]
	v_mfma_f32_16x16x32_bf16 v[72:75], v[144:147], v[222:225], v[72:75]
	s_setprio 1
	s_setprio 0
	v_mfma_f32_16x16x32_bf16 v[132:135], v[148:151], v[188:191], v[132:135]
	v_mfma_f32_16x16x32_bf16 v[128:131], v[174:177], v[188:191], v[128:131]
	v_mfma_f32_16x16x32_bf16 v[116:119], v[148:151], v[202:205], v[116:119]
	v_mfma_f32_16x16x32_bf16 v[108:111], v[174:177], v[202:205], v[108:111]
	v_mfma_f32_16x16x32_bf16 v[84:87], v[148:151], v[210:213], v[84:87]
	v_mfma_f32_16x16x32_bf16 v[80:83], v[174:177], v[210:213], v[80:83]
	v_mfma_f32_16x16x32_bf16 v[68:71], v[148:151], v[218:221], v[68:71]
	v_mfma_f32_16x16x32_bf16 v[64:67], v[174:177], v[218:221], v[64:67]
	v_mfma_f32_16x16x32_bf16 v[132:135], v[170:173], v[198:201], v[132:135]
	v_mfma_f32_16x16x32_bf16 v[128:131], v[178:181], v[198:201], v[128:131]
	v_mfma_f32_16x16x32_bf16 v[116:119], v[170:173], v[206:209], v[116:119]
	v_mfma_f32_16x16x32_bf16 v[108:111], v[178:181], v[206:209], v[108:111]
	v_mfma_f32_16x16x32_bf16 v[84:87], v[170:173], v[214:217], v[84:87]
	v_mfma_f32_16x16x32_bf16 v[80:83], v[178:181], v[214:217], v[80:83]
	v_mfma_f32_16x16x32_bf16 v[68:71], v[170:173], v[222:225], v[68:71]
	v_mfma_f32_16x16x32_bf16 v[64:67], v[178:181], v[222:225], v[64:67]
	s_setprio 1
	s_barrier
; #define PG8_STAGE(bufoff, gbase, voff) do { _Pragma("unroll") for (int _i = 0; _i < 2; ++_i) \
;         __builtin_amdgcn_global_load_lds((const unsigned*)((const char*)(gbase) + (voff)[_i]), (PG8_LAS unsigned*)(lds + (bufoff) + ldsw + _i * 8192), 16, 0, 0); } while (0)
; #define PG8_LDA(dst, b, h) do { _Pragma("unroll") for (int m = 0; m < 4; ++m) _Pragma("unroll") for (int k = 0; k < 2; ++k) dst[m][k] = *(const PG8_LAS bf16x8*)(lds + PG8_SA(b, h) + aoff + m * 2048 + k * 1024); } while (0)
; #define PG8_MMA(ai, bj, At, Bt) do { __builtin_amdgcn_s_setprio(1); _Pragma("unroll") for (int m = 0; m < 4; ++m) _Pragma("unroll") for (int n = 0; n < 2; ++n) _Pragma("unroll") for (int k = 0; k < 2; ++k) \
;         acc[ai][bj][m][n] = __builtin_amdgcn_mfma_f32_16x16x32_bf16(Bt[n][k], At[m][k], acc[ai][bj][m][n], 0, 0, 0); __builtin_amdgcn_s_setprio(0); } while (0)
; #define PG8_WAIT_V(n) asm volatile("s_waitcnt vmcnt(" #n ")" ::: "memory")
; #define PG8_WAIT_L(n) asm volatile("s_waitcnt lgkmcnt(" #n ")" ::: "memory")
; #define PG8_BAR __builtin_amdgcn_s_barrier()
; #define PG8_SCHED __builtin_amdgcn_sched_barrier(0)
; template <class Epi, class Sched, bool ALIGN_EPI = false, bool SP2 = false>
; __device__ __forceinline__ void gemm_phase(PG8_LAS unsigned char* lds, const Gemm g, const Sched& S, const Epi& E) {
;     ...
;         for (int t = 0; t < nt; t += 2) {
;             const bool last = (t == nt - 2);
;             const char* a1 = cA + (size_t)(t + 1) * kstep;
;             const char* a2 = last ? nA : cA + (size_t)(t + 2) * kstep; const char* b2 = last ? nB : cB + (size_t)(t + 2) * kstep;
;             const char* a3 = a2 + (last ? knext : kstep); const char* b3 = b2 + (last ? knext : kstep);
;     ...
;             PG8_LDA(At, 1, 1); PG8_STAGE(PG8_SB(1, 0), b3, voffB); PG8_STAGE(PG8_SB(1, 1), b3 + hstep, voffB); PG8_STAGE(PG8_SA(1, 0), a3, voffA);
;             PG8_WAIT_V(8); PG8_WAIT_L(0); PG8_BAR; PG8_MMA(1, 0, At, B0); PG8_MMA(1, 1, At, B1); PG8_BAR; PG8_SCHED;
	s_add_u32 s42, s42, s44
	s_addc_u32 s43, s43, s45
	s_add_i32 s44, s66, s52
	v_lshl_add_u64 v[182:183], s[42:43], 0, v[154:155]
	s_mov_b32 m0, s44
	ds_read_b128 v[188:191], v187 offset:49152
	ds_read_b128 v[198:201], v187 offset:50176
	ds_read_b128 v[202:205], v187 offset:51200
	ds_read_b128 v[206:209], v187 offset:52224
	ds_read_b128 v[210:213], v187 offset:53248
	ds_read_b128 v[214:217], v187 offset:54272
	ds_read_b128 v[218:221], v187 offset:55296
	ds_read_b128 v[222:225], v187 offset:56320
	global_load_lds_dwordx4 v[182:183], off
	s_add_i32 m0, s44, 0x2000
	v_lshl_add_u64 v[182:183], s[42:43], 0, v[164:165]
	s_add_u32 s42, s42, 0x40000
	s_addc_u32 s43, s43, 0
	s_add_i32 s44, s76, s52
	global_load_lds_dwordx4 v[182:183], off
	v_lshl_add_u64 v[182:183], s[42:43], 0, v[154:155]
	s_mov_b32 m0, s44
	s_nop 0
	global_load_lds_dwordx4 v[182:183], off
	v_lshl_add_u64 v[182:183], s[42:43], 0, v[164:165]
	s_add_i32 m0, s44, 0x2000
	s_nop 0
	global_load_lds_dwordx4 v[182:183], off
	v_lshl_add_u64 v[182:183], s[48:49], 0, v[160:161]
	s_mov_b32 m0, s63
	s_nop 0
	global_load_lds_dwordx4 v[182:183], off
	v_lshl_add_u64 v[182:183], s[48:49], 0, v[162:163]
	s_mov_b32 m0, s65
	s_nop 0
	global_load_lds_dwordx4 v[182:183], off
	s_waitcnt vmcnt(8)
	s_waitcnt lgkmcnt(0)
	s_barrier
	s_setprio 0
	s_waitcnt lgkmcnt(0)
	v_mfma_f32_16x16x32_bf16 v[60:63], v[100:103], v[188:191], v[60:63]
	v_mfma_f32_16x16x32_bf16 v[56:59], v[112:115], v[188:191], v[56:59]
	v_mfma_f32_16x16x32_bf16 v[44:47], v[100:103], v[202:205], v[44:47]
	v_mfma_f32_16x16x32_bf16 v[40:43], v[112:115], v[202:205], v[40:43]
	v_mfma_f32_16x16x32_bf16 v[28:31], v[100:103], v[210:213], v[28:31]
	v_mfma_f32_16x16x32_bf16 v[24:27], v[112:115], v[210:213], v[24:27]
	v_mfma_f32_16x16x32_bf16 v[12:15], v[100:103], v[218:221], v[12:15]
	v_mfma_f32_16x16x32_bf16 v[8:11], v[112:115], v[218:221], v[8:11]
	v_mfma_f32_16x16x32_bf16 v[60:63], v[104:107], v[198:201], v[60:63]
	v_mfma_f32_16x16x32_bf16 v[56:59], v[144:147], v[198:201], v[56:59]
	v_mfma_f32_16x16x32_bf16 v[44:47], v[104:107], v[206:209], v[44:47]
	v_mfma_f32_16x16x32_bf16 v[40:43], v[144:147], v[206:209], v[40:43]
	v_mfma_f32_16x16x32_bf16 v[28:31], v[104:107], v[214:217], v[28:31]
	v_mfma_f32_16x16x32_bf16 v[24:27], v[144:147], v[214:217], v[24:27]
	v_mfma_f32_16x16x32_bf16 v[12:15], v[104:107], v[222:225], v[12:15]
	v_mfma_f32_16x16x32_bf16 v[8:11], v[144:147], v[222:225], v[8:11]
	s_setprio 1
	s_setprio 0
	v_mfma_f32_16x16x32_bf16 v[52:55], v[148:151], v[188:191], v[52:55]
	v_mfma_f32_16x16x32_bf16 v[48:51], v[174:177], v[188:191], v[48:51]
	v_mfma_f32_16x16x32_bf16 v[36:39], v[148:151], v[202:205], v[36:39]
	v_mfma_f32_16x16x32_bf16 v[32:35], v[174:177], v[202:205], v[32:35]
	v_mfma_f32_16x16x32_bf16 v[20:23], v[148:151], v[210:213], v[20:23]
	v_mfma_f32_16x16x32_bf16 v[16:19], v[174:177], v[210:213], v[16:19]
	v_mfma_f32_16x16x32_bf16 v[4:7], v[148:151], v[218:221], v[4:7]
	v_mfma_f32_16x16x32_bf16 v[0:3], v[174:177], v[218:221], v[0:3]
	v_mfma_f32_16x16x32_bf16 v[52:55], v[170:173], v[198:201], v[52:55]
	v_mfma_f32_16x16x32_bf16 v[48:51], v[178:181], v[198:201], v[48:51]
	v_mfma_f32_16x16x32_bf16 v[36:39], v[170:173], v[206:209], v[36:39]
	v_mfma_f32_16x16x32_bf16 v[32:35], v[178:181], v[206:209], v[32:35]
	v_mfma_f32_16x16x32_bf16 v[20:23], v[170:173], v[214:217], v[20:23]
	v_mfma_f32_16x16x32_bf16 v[16:19], v[178:181], v[214:217], v[16:19]
	v_mfma_f32_16x16x32_bf16 v[4:7], v[170:173], v[222:225], v[4:7]
	v_mfma_f32_16x16x32_bf16 v[0:3], v[178:181], v[222:225], v[0:3]
	s_setprio 1
	s_barrier
	s_add_u32 s40, s40, s38
	s_addc_u32 s41, s41, s39
	s_cmp_ge_i32 s59, s1
	s_cbranch_scc1 .LBB0_537

; #define PG8_STAGE(bufoff, gbase, voff) do { _Pragma("unroll") for (int _i = 0; _i < 2; ++_i) \
;         __builtin_amdgcn_global_load_lds((const unsigned*)((const char*)(gbase) + (voff)[_i]), (PG8_LAS unsigned*)(lds + (bufoff) + ldsw + _i * 8192), 16, 0, 0); } while (0)
; #define PG8_LDA(dst, b, h) do { _Pragma("unroll") for (int m = 0; m < 4; ++m) _Pragma("unroll") for (int k = 0; k < 2; ++k) dst[m][k] = *(const PG8_LAS bf16x8*)(lds + PG8_SA(b, h) + aoff + m * 2048 + k * 1024); } while (0)
; #define PG8_LDB(dst, b, h) do { _Pragma("unroll") for (int n = 0; n < 2; ++n) _Pragma("unroll") for (int k = 0; k < 2; ++k) dst[n][k] = *(const PG8_LAS bf16x8*)(lds + PG8_SB(b, h) + boff + n * 2048 + k * 1024); } while (0)
; #define PG8_MMA(ai, bj, At, Bt) do { __builtin_amdgcn_s_setprio(1); _Pragma("unroll") for (int m = 0; m < 4; ++m) _Pragma("unroll") for (int n = 0; n < 2; ++n) _Pragma("unroll") for (int k = 0; k < 2; ++k) \
;         acc[ai][bj][m][n] = __builtin_amdgcn_mfma_f32_16x16x32_bf16(Bt[n][k], At[m][k], acc[ai][bj][m][n], 0, 0, 0); __builtin_amdgcn_s_setprio(0); } while (0)
; #define PG8_WAIT_V(n) asm volatile("s_waitcnt vmcnt(" #n ")" ::: "memory")
; #define PG8_WAIT_L(n) asm volatile("s_waitcnt lgkmcnt(" #n ")" ::: "memory")
; #define PG8_BAR __builtin_amdgcn_s_barrier()
; #define PG8_SCHED __builtin_amdgcn_sched_barrier(0)
; template <class Epi, class Sched, bool ALIGN_EPI = false, bool SP2 = false>
; __device__ __forceinline__ void gemm_phase(PG8_LAS unsigned char* lds, const Gemm g, const Sched& S, const Epi& E) {
;     ...
;             PG8_LDB(B0, 0, 0); PG8_LDB(B1, 0, 1); PG8_SCHED; PG8_LDA(At, 0, 0); PG8_STAGE(PG8_SA(1, 1), a1 + hstep, voffA);
;             PG8_WAIT_V(8); PG8_WAIT_L(0); PG8_BAR; PG8_MMA(0, 0, At, B0); PG8_MMA(0, 1, At, B1); PG8_BAR; PG8_SCHED;
;             PG8_LDA(At, 0, 1); PG8_STAGE(PG8_SB(0, 0), b2, voffB); PG8_STAGE(PG8_SB(0, 1), b2 + hstep, voffB); PG8_STAGE(PG8_SA(0, 0), a2, voffA);
.LBB0_799:
	s_or_b32 s44, s15, 1
	s_mul_i32 s45, s31, s44
	s_mul_hi_u32 s57, s30, s44
	s_add_i32 s57, s57, s45
	s_mul_i32 s44, s30, s44
	s_add_u32 s59, s28, s44
	s_addc_u32 s57, s29, s57
	s_add_u32 s44, s42, s40
	s_addc_u32 s45, s43, s41
	s_add_i32 s62, 0, 0x10000
	v_add_u32_e32 v134, s62, v137
	s_add_i32 s63, 0, 0x14000
	ds_read_b128 v[140:143], v134
	ds_read_b128 v[144:147], v134 offset:1024
	ds_read_b128 v[148:151], v134 offset:2048
	ds_read_b128 v[158:161], v134 offset:3072
	v_add_u32_e32 v134, s63, v137
	ds_read_b128 v[162:165], v134
	ds_read_b128 v[166:169], v134 offset:1024
	ds_read_b128 v[170:173], v134 offset:2048
	ds_read_b128 v[174:177], v134 offset:3072
	s_add_u32 s60, s59, 0x40000
	s_addc_u32 s61, s57, 0
	v_lshl_add_u64 v[134:135], s[60:61], 0, v[132:133]
	s_add_i32 m0, s23, 0xc000
	ds_read_b128 v[178:181], v139
	ds_read_b128 v[182:185], v139 offset:1024
	ds_read_b128 v[186:189], v139 offset:2048
	ds_read_b128 v[190:193], v139 offset:3072
	ds_read_b128 v[198:201], v139 offset:4096
	ds_read_b128 v[202:205], v139 offset:5120
	ds_read_b128 v[206:209], v139 offset:6144
	ds_read_b128 v[210:213], v139 offset:7168
	global_load_lds_dwordx4 v[134:135], off
	v_lshl_add_u64 v[134:135], s[60:61], 0, v[130:131]
	s_add_i32 m0, s23, 0xe000
	s_nop 0
	global_load_lds_dwordx4 v[134:135], off
	s_waitcnt vmcnt(8)
	s_waitcnt lgkmcnt(0)
	s_barrier
	s_setprio 0
	s_waitcnt lgkmcnt(0)
	v_mfma_f32_16x16x32_bf16 v[124:127], v[140:143], v[178:181], v[124:127]
	v_mfma_f32_16x16x32_bf16 v[120:123], v[148:151], v[178:181], v[120:123]
	v_mfma_f32_16x16x32_bf16 v[108:111], v[140:143], v[186:189], v[108:111]
	v_mfma_f32_16x16x32_bf16 v[104:107], v[148:151], v[186:189], v[104:107]
	v_mfma_f32_16x16x32_bf16 v[92:95], v[140:143], v[198:201], v[92:95]
	v_mfma_f32_16x16x32_bf16 v[88:91], v[148:151], v[198:201], v[88:91]
	v_mfma_f32_16x16x32_bf16 v[76:79], v[140:143], v[206:209], v[76:79]
	v_mfma_f32_16x16x32_bf16 v[72:75], v[148:151], v[206:209], v[72:75]
	v_mfma_f32_16x16x32_bf16 v[124:127], v[144:147], v[182:185], v[124:127]
	v_mfma_f32_16x16x32_bf16 v[120:123], v[158:161], v[182:185], v[120:123]
	v_mfma_f32_16x16x32_bf16 v[108:111], v[144:147], v[190:193], v[108:111]
	v_mfma_f32_16x16x32_bf16 v[104:107], v[158:161], v[190:193], v[104:107]
	v_mfma_f32_16x16x32_bf16 v[92:95], v[144:147], v[202:205], v[92:95]
	v_mfma_f32_16x16x32_bf16 v[88:91], v[158:161], v[202:205], v[88:91]
	v_mfma_f32_16x16x32_bf16 v[76:79], v[144:147], v[210:213], v[76:79]
	v_mfma_f32_16x16x32_bf16 v[72:75], v[158:161], v[210:213], v[72:75]
	s_setprio 1
	s_setprio 0
	v_mfma_f32_16x16x32_bf16 v[116:119], v[162:165], v[178:181], v[116:119]
	v_mfma_f32_16x16x32_bf16 v[112:115], v[170:173], v[178:181], v[112:115]
	v_mfma_f32_16x16x32_bf16 v[100:103], v[162:165], v[186:189], v[100:103]
	v_mfma_f32_16x16x32_bf16 v[96:99], v[170:173], v[186:189], v[96:99]
	v_mfma_f32_16x16x32_bf16 v[84:87], v[162:165], v[198:201], v[84:87]
	v_mfma_f32_16x16x32_bf16 v[80:83], v[170:173], v[198:201], v[80:83]
	v_mfma_f32_16x16x32_bf16 v[68:71], v[162:165], v[206:209], v[68:71]
	v_mfma_f32_16x16x32_bf16 v[64:67], v[170:173], v[206:209], v[64:67]
	v_mfma_f32_16x16x32_bf16 v[116:119], v[166:169], v[182:185], v[116:119]
	v_mfma_f32_16x16x32_bf16 v[112:115], v[174:177], v[182:185], v[112:115]
	v_mfma_f32_16x16x32_bf16 v[100:103], v[166:169], v[190:193], v[100:103]
	v_mfma_f32_16x16x32_bf16 v[96:99], v[174:177], v[190:193], v[96:99]
	v_mfma_f32_16x16x32_bf16 v[84:87], v[166:169], v[202:205], v[84:87]
	v_mfma_f32_16x16x32_bf16 v[80:83], v[174:177], v[202:205], v[80:83]
	v_mfma_f32_16x16x32_bf16 v[68:71], v[166:169], v[210:213], v[68:71]
	v_mfma_f32_16x16x32_bf16 v[64:67], v[174:177], v[210:213], v[64:67]
	s_setprio 1
	s_barrier
	s_add_i32 s57, s62, s51
	v_lshl_add_u64 v[134:135], s[38:39], 0, v[154:155]
	s_mov_b32 m0, s57
	ds_read_b128 v[178:181], v139 offset:16384
	ds_read_b128 v[182:185], v139 offset:17408
	ds_read_b128 v[186:189], v139 offset:18432
	ds_read_b128 v[190:193], v139 offset:19456
	ds_read_b128 v[198:201], v139 offset:20480
	ds_read_b128 v[202:205], v139 offset:21504
	ds_read_b128 v[206:209], v139 offset:22528
	ds_read_b128 v[210:213], v139 offset:23552
	global_load_lds_dwordx4 v[134:135], off
	s_add_i32 m0, s57, 0x2000
	s_add_u32 s60, s38, 0x40000
	v_lshl_add_u64 v[134:135], s[38:39], 0, v[128:129]
	s_addc_u32 s61, s39, 0
	s_add_i32 s57, s63, s51
	global_load_lds_dwordx4 v[134:135], off
	v_lshl_add_u64 v[134:135], s[60:61], 0, v[154:155]
	s_mov_b32 m0, s57
	s_nop 0
	global_load_lds_dwordx4 v[134:135], off
	v_lshl_add_u64 v[134:135], s[60:61], 0, v[128:129]
	s_add_i32 m0, s57, 0x2000
	s_nop 0
	global_load_lds_dwordx4 v[134:135], off
	v_lshl_add_u64 v[134:135], s[42:43], 0, v[132:133]
	s_mov_b32 m0, s23
	s_nop 0
	global_load_lds_dwordx4 v[134:135], off
	v_lshl_add_u64 v[134:135], s[42:43], 0, v[130:131]
	s_mov_b32 m0, s25
	s_nop 0
	global_load_lds_dwordx4 v[134:135], off
	s_waitcnt vmcnt(8)
	s_waitcnt lgkmcnt(0)
	s_barrier
; #define PG8_STAGE(bufoff, gbase, voff) do { _Pragma("unroll") for (int _i = 0; _i < 2; ++_i) \
;         __builtin_amdgcn_global_load_lds((const unsigned*)((const char*)(gbase) + (voff)[_i]), (PG8_LAS unsigned*)(lds + (bufoff) + ldsw + _i * 8192), 16, 0, 0); } while (0)
; #define PG8_LDA(dst, b, h) do { _Pragma("unroll") for (int m = 0; m < 4; ++m) _Pragma("unroll") for (int k = 0; k < 2; ++k) dst[m][k] = *(const PG8_LAS bf16x8*)(lds + PG8_SA(b, h) + aoff + m * 2048 + k * 1024); } while (0)
; #define PG8_LDB(dst, b, h) do { _Pragma("unroll") for (int n = 0; n < 2; ++n) _Pragma("unroll") for (int k = 0; k < 2; ++k) dst[n][k] = *(const PG8_LAS bf16x8*)(lds + PG8_SB(b, h) + boff + n * 2048 + k * 1024); } while (0)
; #define PG8_MMA(ai, bj, At, Bt) do { __builtin_amdgcn_s_setprio(1); _Pragma("unroll") for (int m = 0; m < 4; ++m) _Pragma("unroll") for (int n = 0; n < 2; ++n) _Pragma("unroll") for (int k = 0; k < 2; ++k) \
;         acc[ai][bj][m][n] = __builtin_amdgcn_mfma_f32_16x16x32_bf16(Bt[n][k], At[m][k], acc[ai][bj][m][n], 0, 0, 0); __builtin_amdgcn_s_setprio(0); } while (0)
; #define PG8_WAIT_V(n) asm volatile("s_waitcnt vmcnt(" #n ")" ::: "memory")
; #define PG8_WAIT_L(n) asm volatile("s_waitcnt lgkmcnt(" #n ")" ::: "memory")
; #define PG8_BAR __builtin_amdgcn_s_barrier()
; #define PG8_SCHED __builtin_amdgcn_sched_barrier(0)
; template <class Epi, class Sched, bool ALIGN_EPI = false, bool SP2 = false>
; __device__ __forceinline__ void gemm_phase(PG8_LAS unsigned char* lds, const Gemm g, const Sched& S, const Epi& E) {
;     ...
;             PG8_WAIT_V(8); PG8_WAIT_L(0); PG8_BAR; PG8_MMA(1, 0, At, B0); PG8_MMA(1, 1, At, B1); PG8_BAR; PG8_SCHED;
;             PG8_LDB(B0, 1, 0); PG8_LDB(B1, 1, 1); PG8_SCHED; PG8_LDA(At, 1, 0); PG8_STAGE(PG8_SA(0, 1), a2 + hstep, voffA);
;             PG8_WAIT_V(8); PG8_WAIT_L(0); PG8_BAR; PG8_MMA(0, 0, At, B0); PG8_MMA(0, 1, At, B1); PG8_BAR; PG8_SCHED;
	s_setprio 0
	s_waitcnt lgkmcnt(0)
	v_mfma_f32_16x16x32_bf16 v[60:63], v[140:143], v[178:181], v[60:63]
	v_mfma_f32_16x16x32_bf16 v[56:59], v[148:151], v[178:181], v[56:59]
	v_mfma_f32_16x16x32_bf16 v[44:47], v[140:143], v[186:189], v[44:47]
	v_mfma_f32_16x16x32_bf16 v[40:43], v[148:151], v[186:189], v[40:43]
	v_mfma_f32_16x16x32_bf16 v[28:31], v[140:143], v[198:201], v[28:31]
	v_mfma_f32_16x16x32_bf16 v[24:27], v[148:151], v[198:201], v[24:27]
	v_mfma_f32_16x16x32_bf16 v[12:15], v[140:143], v[206:209], v[12:15]
	v_mfma_f32_16x16x32_bf16 v[8:11], v[148:151], v[206:209], v[8:11]
	v_mfma_f32_16x16x32_bf16 v[60:63], v[144:147], v[182:185], v[60:63]
	v_mfma_f32_16x16x32_bf16 v[56:59], v[158:161], v[182:185], v[56:59]
	v_mfma_f32_16x16x32_bf16 v[44:47], v[144:147], v[190:193], v[44:47]
	v_mfma_f32_16x16x32_bf16 v[40:43], v[158:161], v[190:193], v[40:43]
	v_mfma_f32_16x16x32_bf16 v[28:31], v[144:147], v[202:205], v[28:31]
	v_mfma_f32_16x16x32_bf16 v[24:27], v[158:161], v[202:205], v[24:27]
	v_mfma_f32_16x16x32_bf16 v[12:15], v[144:147], v[210:213], v[12:15]
	v_mfma_f32_16x16x32_bf16 v[8:11], v[158:161], v[210:213], v[8:11]
	s_setprio 1
	s_setprio 0
	v_mfma_f32_16x16x32_bf16 v[52:55], v[162:165], v[178:181], v[52:55]
	v_mfma_f32_16x16x32_bf16 v[48:51], v[170:173], v[178:181], v[48:51]
	v_mfma_f32_16x16x32_bf16 v[36:39], v[162:165], v[186:189], v[36:39]
	v_mfma_f32_16x16x32_bf16 v[32:35], v[170:173], v[186:189], v[32:35]
	v_mfma_f32_16x16x32_bf16 v[20:23], v[162:165], v[198:201], v[20:23]
	v_mfma_f32_16x16x32_bf16 v[16:19], v[170:173], v[198:201], v[16:19]
	v_mfma_f32_16x16x32_bf16 v[4:7], v[162:165], v[206:209], v[4:7]
	v_mfma_f32_16x16x32_bf16 v[0:3], v[170:173], v[206:209], v[0:3]
	v_mfma_f32_16x16x32_bf16 v[52:55], v[166:169], v[182:185], v[52:55]
	v_mfma_f32_16x16x32_bf16 v[48:51], v[174:177], v[182:185], v[48:51]
	v_mfma_f32_16x16x32_bf16 v[36:39], v[166:169], v[190:193], v[36:39]
	v_mfma_f32_16x16x32_bf16 v[32:35], v[174:177], v[190:193], v[32:35]
	v_mfma_f32_16x16x32_bf16 v[20:23], v[166:169], v[202:205], v[20:23]
	v_mfma_f32_16x16x32_bf16 v[16:19], v[174:177], v[202:205], v[16:19]
	v_mfma_f32_16x16x32_bf16 v[4:7], v[166:169], v[210:213], v[4:7]
	v_mfma_f32_16x16x32_bf16 v[0:3], v[174:177], v[210:213], v[0:3]
	s_setprio 1
	s_barrier
	s_add_i32 s57, 0, 0x18000
	v_add_u32_e32 v134, s57, v137
	s_add_i32 s59, 0, 0x1c000
	ds_read_b128 v[140:143], v134
	ds_read_b128 v[144:147], v134 offset:1024
	ds_read_b128 v[148:151], v134 offset:2048
	ds_read_b128 v[158:161], v134 offset:3072
	v_add_u32_e32 v134, s59, v137
	ds_read_b128 v[162:165], v134
	ds_read_b128 v[166:169], v134 offset:1024
	ds_read_b128 v[170:173], v134 offset:2048
	ds_read_b128 v[174:177], v134 offset:3072
	s_add_u32 s42, s42, 0x40000
	s_addc_u32 s43, s43, 0
	s_mov_b32 m0, s52
	v_lshl_add_u64 v[134:135], s[42:43], 0, v[132:133]
	ds_read_b128 v[178:181], v139 offset:32768
	ds_read_b128 v[182:185], v139 offset:33792
	ds_read_b128 v[186:189], v139 offset:34816
	ds_read_b128 v[190:193], v139 offset:35840
	ds_read_b128 v[198:201], v139 offset:36864
	ds_read_b128 v[202:205], v139 offset:37888
	ds_read_b128 v[206:209], v139 offset:38912
	ds_read_b128 v[210:213], v139 offset:39936
	global_load_lds_dwordx4 v[134:135], off
	v_lshl_add_u64 v[134:135], s[42:43], 0, v[130:131]
	s_mov_b32 m0, s53
	s_nop 0
	global_load_lds_dwordx4 v[134:135], off
	s_waitcnt vmcnt(8)
	s_waitcnt lgkmcnt(0)
	s_barrier
	s_setprio 0
	s_waitcnt lgkmcnt(0)
	v_mfma_f32_16x16x32_bf16 v[124:127], v[140:143], v[178:181], v[124:127]
	v_mfma_f32_16x16x32_bf16 v[120:123], v[148:151], v[178:181], v[120:123]
	v_mfma_f32_16x16x32_bf16 v[108:111], v[140:143], v[186:189], v[108:111]
	v_mfma_f32_16x16x32_bf16 v[104:107], v[148:151], v[186:189], v[104:107]
	v_mfma_f32_16x16x32_bf16 v[92:95], v[140:143], v[198:201], v[92:95]
	v_mfma_f32_16x16x32_bf16 v[88:91], v[148:151], v[198:201], v[88:91]
	v_mfma_f32_16x16x32_bf16 v[76:79], v[140:143], v[206:209], v[76:79]
	v_mfma_f32_16x16x32_bf16 v[72:75], v[148:151], v[206:209], v[72:75]
	v_mfma_f32_16x16x32_bf16 v[124:127], v[144:147], v[182:185], v[124:127]
	v_mfma_f32_16x16x32_bf16 v[120:123], v[158:161], v[182:185], v[120:123]
	v_mfma_f32_16x16x32_bf16 v[108:111], v[144:147], v[190:193], v[108:111]
	v_mfma_f32_16x16x32_bf16 v[104:107], v[158:161], v[190:193], v[104:107]
	v_mfma_f32_16x16x32_bf16 v[92:95], v[144:147], v[202:205], v[92:95]
	v_mfma_f32_16x16x32_bf16 v[88:91], v[158:161], v[202:205], v[88:91]
	v_mfma_f32_16x16x32_bf16 v[76:79], v[144:147], v[210:213], v[76:79]
	v_mfma_f32_16x16x32_bf16 v[72:75], v[158:161], v[210:213], v[72:75]
	s_setprio 1
	s_setprio 0
	v_mfma_f32_16x16x32_bf16 v[116:119], v[162:165], v[178:181], v[116:119]
	v_mfma_f32_16x16x32_bf16 v[112:115], v[170:173], v[178:181], v[112:115]
	v_mfma_f32_16x16x32_bf16 v[100:103], v[162:165], v[186:189], v[100:103]
	v_mfma_f32_16x16x32_bf16 v[96:99], v[170:173], v[186:189], v[96:99]
	v_mfma_f32_16x16x32_bf16 v[84:87], v[162:165], v[198:201], v[84:87]
	v_mfma_f32_16x16x32_bf16 v[80:83], v[170:173], v[198:201], v[80:83]
	v_mfma_f32_16x16x32_bf16 v[68:71], v[162:165], v[206:209], v[68:71]
	v_mfma_f32_16x16x32_bf16 v[64:67], v[170:173], v[206:209], v[64:67]
	v_mfma_f32_16x16x32_bf16 v[116:119], v[166:169], v[182:185], v[116:119]
	v_mfma_f32_16x16x32_bf16 v[112:115], v[174:177], v[182:185], v[112:115]
	v_mfma_f32_16x16x32_bf16 v[100:103], v[166:169], v[190:193], v[100:103]
	v_mfma_f32_16x16x32_bf16 v[96:99], v[174:177], v[190:193], v[96:99]
	v_mfma_f32_16x16x32_bf16 v[84:87], v[166:169], v[202:205], v[84:87]
	v_mfma_f32_16x16x32_bf16 v[80:83], v[174:177], v[202:205], v[80:83]
	v_mfma_f32_16x16x32_bf16 v[68:71], v[166:169], v[210:213], v[68:71]
	v_mfma_f32_16x16x32_bf16 v[64:67], v[174:177], v[210:213], v[64:67]
	s_setprio 1
	s_barrier
; #define PG8_STAGE(bufoff, gbase, voff) do { _Pragma("unroll") for (int _i = 0; _i < 2; ++_i) \
;         __builtin_amdgcn_global_load_lds((const unsigned*)((const char*)(gbase) + (voff)[_i]), (PG8_LAS unsigned*)(lds + (bufoff) + ldsw + _i * 8192), 16, 0, 0); } while (0)
; #define PG8_LDA(dst, b, h) do { _Pragma("unroll") for (int m = 0; m < 4; ++m) _Pragma("unroll") for (int k = 0; k < 2; ++k) dst[m][k] = *(const PG8_LAS bf16x8*)(lds + PG8_SA(b, h) + aoff + m * 2048 + k * 1024); } while (0)
; #define PG8_MMA(ai, bj, At, Bt) do { __builtin_amdgcn_s_setprio(1); _Pragma("unroll") for (int m = 0; m < 4; ++m) _Pragma("unroll") for (int n = 0; n < 2; ++n) _Pragma("unroll") for (int k = 0; k < 2; ++k) \
;         acc[ai][bj][m][n] = __builtin_amdgcn_mfma_f32_16x16x32_bf16(Bt[n][k], At[m][k], acc[ai][bj][m][n], 0, 0, 0); __builtin_amdgcn_s_setprio(0); } while (0)
; #define PG8_WAIT_V(n) asm volatile("s_waitcnt vmcnt(" #n ")" ::: "memory")
; #define PG8_WAIT_L(n) asm volatile("s_waitcnt lgkmcnt(" #n ")" ::: "memory")
; #define PG8_BAR __builtin_amdgcn_s_barrier()
; #define PG8_SCHED __builtin_amdgcn_sched_barrier(0)
; template <class Epi, class Sched, bool ALIGN_EPI = false, bool SP2 = false>
; __device__ __forceinline__ void gemm_phase(PG8_LAS unsigned char* lds, const Gemm g, const Sched& S, const Epi& E) {
;     ...
;         for (int t = 0; t < nt; t += 2) {
;             const bool last = (t == nt - 2);
;             const char* a1 = cA + (size_t)(t + 1) * kstep;
;             const char* a2 = last ? nA : cA + (size_t)(t + 2) * kstep; const char* b2 = last ? nB : cB + (size_t)(t + 2) * kstep;
;             const char* a3 = a2 + (last ? knext : kstep); const char* b3 = b2 + (last ? knext : kstep);
;     ...
;             PG8_LDA(At, 1, 1); PG8_STAGE(PG8_SB(1, 0), b3, voffB); PG8_STAGE(PG8_SB(1, 1), b3 + hstep, voffB); PG8_STAGE(PG8_SA(1, 0), a3, voffA);
;             PG8_WAIT_V(8); PG8_WAIT_L(0); PG8_BAR; PG8_MMA(1, 0, At, B0); PG8_MMA(1, 1, At, B1); PG8_BAR; PG8_SCHED;
	s_add_u32 s38, s38, s40
	s_addc_u32 s39, s39, s41
	s_add_i32 s40, s57, s51
	v_lshl_add_u64 v[134:135], s[38:39], 0, v[154:155]
	s_mov_b32 m0, s40
	ds_read_b128 v[178:181], v139 offset:49152
	ds_read_b128 v[182:185], v139 offset:50176
	ds_read_b128 v[186:189], v139 offset:51200
	ds_read_b128 v[190:193], v139 offset:52224
	ds_read_b128 v[198:201], v139 offset:53248
	ds_read_b128 v[202:205], v139 offset:54272
	ds_read_b128 v[206:209], v139 offset:55296
	ds_read_b128 v[210:213], v139 offset:56320
	global_load_lds_dwordx4 v[134:135], off
	s_add_i32 m0, s40, 0x2000
	v_lshl_add_u64 v[134:135], s[38:39], 0, v[128:129]
	s_add_u32 s38, s38, 0x40000
	s_addc_u32 s39, s39, 0
	s_add_i32 s40, s59, s51
	global_load_lds_dwordx4 v[134:135], off
	v_lshl_add_u64 v[134:135], s[38:39], 0, v[154:155]
	s_mov_b32 m0, s40
	s_nop 0
	global_load_lds_dwordx4 v[134:135], off
	v_lshl_add_u64 v[134:135], s[38:39], 0, v[128:129]
	s_add_i32 m0, s40, 0x2000
	s_nop 0
	global_load_lds_dwordx4 v[134:135], off
	v_lshl_add_u64 v[134:135], s[44:45], 0, v[132:133]
	s_mov_b32 m0, s54
	s_nop 0
	global_load_lds_dwordx4 v[134:135], off
	v_lshl_add_u64 v[134:135], s[44:45], 0, v[130:131]
	s_mov_b32 m0, s55
	s_nop 0
	global_load_lds_dwordx4 v[134:135], off
	s_waitcnt vmcnt(8)
	s_waitcnt lgkmcnt(0)
	s_barrier
	s_setprio 0
	s_waitcnt lgkmcnt(0)
	v_mfma_f32_16x16x32_bf16 v[60:63], v[140:143], v[178:181], v[60:63]
	v_mfma_f32_16x16x32_bf16 v[56:59], v[148:151], v[178:181], v[56:59]
	v_mfma_f32_16x16x32_bf16 v[44:47], v[140:143], v[186:189], v[44:47]
	v_mfma_f32_16x16x32_bf16 v[40:43], v[148:151], v[186:189], v[40:43]
	v_mfma_f32_16x16x32_bf16 v[28:31], v[140:143], v[198:201], v[28:31]
	v_mfma_f32_16x16x32_bf16 v[24:27], v[148:151], v[198:201], v[24:27]
	v_mfma_f32_16x16x32_bf16 v[12:15], v[140:143], v[206:209], v[12:15]
	v_mfma_f32_16x16x32_bf16 v[8:11], v[148:151], v[206:209], v[8:11]
	v_mfma_f32_16x16x32_bf16 v[60:63], v[144:147], v[182:185], v[60:63]
	v_mfma_f32_16x16x32_bf16 v[56:59], v[158:161], v[182:185], v[56:59]
	v_mfma_f32_16x16x32_bf16 v[44:47], v[144:147], v[190:193], v[44:47]
	v_mfma_f32_16x16x32_bf16 v[40:43], v[158:161], v[190:193], v[40:43]
	v_mfma_f32_16x16x32_bf16 v[28:31], v[144:147], v[202:205], v[28:31]
	v_mfma_f32_16x16x32_bf16 v[24:27], v[158:161], v[202:205], v[24:27]
	v_mfma_f32_16x16x32_bf16 v[12:15], v[144:147], v[210:213], v[12:15]
	v_mfma_f32_16x16x32_bf16 v[8:11], v[158:161], v[210:213], v[8:11]
	s_setprio 1
	s_setprio 0
	v_mfma_f32_16x16x32_bf16 v[52:55], v[162:165], v[178:181], v[52:55]
	v_mfma_f32_16x16x32_bf16 v[48:51], v[170:173], v[178:181], v[48:51]
	v_mfma_f32_16x16x32_bf16 v[36:39], v[162:165], v[186:189], v[36:39]
	v_mfma_f32_16x16x32_bf16 v[32:35], v[170:173], v[186:189], v[32:35]
	v_mfma_f32_16x16x32_bf16 v[20:23], v[162:165], v[198:201], v[20:23]
	v_mfma_f32_16x16x32_bf16 v[16:19], v[170:173], v[198:201], v[16:19]
	v_mfma_f32_16x16x32_bf16 v[4:7], v[162:165], v[206:209], v[4:7]
	v_mfma_f32_16x16x32_bf16 v[0:3], v[170:173], v[206:209], v[0:3]
	v_mfma_f32_16x16x32_bf16 v[52:55], v[166:169], v[182:185], v[52:55]
	v_mfma_f32_16x16x32_bf16 v[48:51], v[174:177], v[182:185], v[48:51]
	v_mfma_f32_16x16x32_bf16 v[36:39], v[166:169], v[190:193], v[36:39]
	v_mfma_f32_16x16x32_bf16 v[32:35], v[174:177], v[190:193], v[32:35]
	v_mfma_f32_16x16x32_bf16 v[20:23], v[166:169], v[202:205], v[20:23]
	v_mfma_f32_16x16x32_bf16 v[16:19], v[174:177], v[202:205], v[16:19]
	v_mfma_f32_16x16x32_bf16 v[4:7], v[166:169], v[210:213], v[4:7]
	v_mfma_f32_16x16x32_bf16 v[0:3], v[174:177], v[210:213], v[0:3]
	s_setprio 1
	s_barrier
	s_cmp_gt_u32 s15, 13
	s_mov_b32 s15, s13
	s_cbranch_scc1 .LBB0_804

; #define PG8_STAGE(bufoff, gbase, voff) do { _Pragma("unroll") for (int _i = 0; _i < 2; ++_i) \
;         __builtin_amdgcn_global_load_lds((const unsigned*)((const char*)(gbase) + (voff)[_i]), (PG8_LAS unsigned*)(lds + (bufoff) + ldsw + _i * 8192), 16, 0, 0); } while (0)
; #define PG8_LDA(dst, b, h) do { _Pragma("unroll") for (int m = 0; m < 4; ++m) _Pragma("unroll") for (int k = 0; k < 2; ++k) dst[m][k] = *(const PG8_LAS bf16x8*)(lds + PG8_SA(b, h) + aoff + m * 2048 + k * 1024); } while (0)
; #define PG8_LDB(dst, b, h) do { _Pragma("unroll") for (int n = 0; n < 2; ++n) _Pragma("unroll") for (int k = 0; k < 2; ++k) dst[n][k] = *(const PG8_LAS bf16x8*)(lds + PG8_SB(b, h) + boff + n * 2048 + k * 1024); } while (0)
; #define PG8_MMA(ai, bj, At, Bt) do { __builtin_amdgcn_s_setprio(1); _Pragma("unroll") for (int m = 0; m < 4; ++m) _Pragma("unroll") for (int n = 0; n < 2; ++n) _Pragma("unroll") for (int k = 0; k < 2; ++k) \
;         acc[ai][bj][m][n] = __builtin_amdgcn_mfma_f32_16x16x32_bf16(Bt[n][k], At[m][k], acc[ai][bj][m][n], 0, 0, 0); __builtin_amdgcn_s_setprio(0); } while (0)
; #define PG8_WAIT_V(n) asm volatile("s_waitcnt vmcnt(" #n ")" ::: "memory")
; #define PG8_WAIT_L(n) asm volatile("s_waitcnt lgkmcnt(" #n ")" ::: "memory")
; #define PG8_BAR __builtin_amdgcn_s_barrier()
; #define PG8_SCHED __builtin_amdgcn_sched_barrier(0)
; template <class Epi, class Sched, bool ALIGN_EPI = false, bool SP2 = false>
; __device__ __forceinline__ void gemm_phase(PG8_LAS unsigned char* lds, const Gemm g, const Sched& S, const Epi& E) {
;     ...
;             PG8_LDB(B0, 0, 0); PG8_LDB(B1, 0, 1); PG8_SCHED; PG8_LDA(At, 0, 0); PG8_STAGE(PG8_SA(1, 1), a1 + hstep, voffA);
;             PG8_WAIT_V(8); PG8_WAIT_L(0); PG8_BAR; PG8_MMA(0, 0, At, B0); PG8_MMA(0, 1, At, B1); PG8_BAR; PG8_SCHED;
;             PG8_LDA(At, 0, 1); PG8_STAGE(PG8_SB(0, 0), b2, voffB); PG8_STAGE(PG8_SB(0, 1), b2 + hstep, voffB); PG8_STAGE(PG8_SA(0, 0), a2, voffA);
.LBB0_908:
	s_add_i32 s17, 0, 0x10000
	s_add_i32 s19, 0, 0x14000
	v_add_u32_e32 v148, s17, v187
	v_add_u32_e32 v190, s19, v187
	ds_read_b128 v[96:99], v148
	ds_read_b128 v[100:103], v148 offset:1024
	ds_read_b128 v[144:147], v148 offset:2048
	ds_read_b128 v[148:151], v148 offset:3072
	ds_read_b128 v[174:177], v190
	ds_read_b128 v[178:181], v190 offset:1024
	ds_read_b128 v[182:185], v190 offset:2048
	ds_read_b128 v[190:193], v190 offset:3072
	s_add_i32 s11, s11, 2
	v_lshl_add_u64 v[230:231], v[82:83], 0, v[166:167]
	s_add_i32 m0, s35, 0xc000
	ds_read_b128 v[198:201], v189
	ds_read_b128 v[202:205], v189 offset:1024
	ds_read_b128 v[206:209], v189 offset:2048
	ds_read_b128 v[210:213], v189 offset:3072
	ds_read_b128 v[214:217], v189 offset:4096
	ds_read_b128 v[218:221], v189 offset:5120
	ds_read_b128 v[222:225], v189 offset:6144
	ds_read_b128 v[226:229], v189 offset:7168
	global_load_lds_dwordx4 v[230:231], off
	v_lshl_add_u64 v[230:231], v[82:83], 0, v[168:169]
	s_add_i32 m0, s35, 0xe000
	s_nop 0
	global_load_lds_dwordx4 v[230:231], off
	s_waitcnt vmcnt(8)
	s_waitcnt lgkmcnt(0)
	s_barrier
	s_setprio 0
	s_waitcnt lgkmcnt(0)
	v_mfma_f32_16x16x32_bf16 v[140:143], v[96:99], v[198:201], v[140:143]
	v_mfma_f32_16x16x32_bf16 v[136:139], v[144:147], v[198:201], v[136:139]
	v_mfma_f32_16x16x32_bf16 v[124:127], v[96:99], v[206:209], v[124:127]
	v_mfma_f32_16x16x32_bf16 v[120:123], v[144:147], v[206:209], v[120:123]
	v_mfma_f32_16x16x32_bf16 v[108:111], v[96:99], v[214:217], v[108:111]
	v_mfma_f32_16x16x32_bf16 v[104:107], v[144:147], v[214:217], v[104:107]
	v_mfma_f32_16x16x32_bf16 v[76:79], v[96:99], v[222:225], v[76:79]
	v_mfma_f32_16x16x32_bf16 v[72:75], v[144:147], v[222:225], v[72:75]
	v_mfma_f32_16x16x32_bf16 v[140:143], v[100:103], v[202:205], v[140:143]
	v_mfma_f32_16x16x32_bf16 v[136:139], v[148:151], v[202:205], v[136:139]
	v_mfma_f32_16x16x32_bf16 v[124:127], v[100:103], v[210:213], v[124:127]
	v_mfma_f32_16x16x32_bf16 v[120:123], v[148:151], v[210:213], v[120:123]
	v_mfma_f32_16x16x32_bf16 v[108:111], v[100:103], v[218:221], v[108:111]
	v_mfma_f32_16x16x32_bf16 v[104:107], v[148:151], v[218:221], v[104:107]
	v_mfma_f32_16x16x32_bf16 v[76:79], v[100:103], v[226:229], v[76:79]
	v_mfma_f32_16x16x32_bf16 v[72:75], v[148:151], v[226:229], v[72:75]
	s_setprio 1
	s_setprio 0
	v_mfma_f32_16x16x32_bf16 v[132:135], v[174:177], v[198:201], v[132:135]
	v_mfma_f32_16x16x32_bf16 v[128:131], v[182:185], v[198:201], v[128:131]
	v_mfma_f32_16x16x32_bf16 v[116:119], v[174:177], v[206:209], v[116:119]
	v_mfma_f32_16x16x32_bf16 v[112:115], v[182:185], v[206:209], v[112:115]
	v_mfma_f32_16x16x32_bf16 v[92:95], v[174:177], v[214:217], v[92:95]
	v_mfma_f32_16x16x32_bf16 v[84:87], v[182:185], v[214:217], v[84:87]
	v_mfma_f32_16x16x32_bf16 v[68:71], v[174:177], v[222:225], v[68:71]
	v_mfma_f32_16x16x32_bf16 v[64:67], v[182:185], v[222:225], v[64:67]
	v_mfma_f32_16x16x32_bf16 v[132:135], v[178:181], v[202:205], v[132:135]
	v_mfma_f32_16x16x32_bf16 v[128:131], v[190:193], v[202:205], v[128:131]
	v_mfma_f32_16x16x32_bf16 v[116:119], v[178:181], v[210:213], v[116:119]
	v_mfma_f32_16x16x32_bf16 v[112:115], v[190:193], v[210:213], v[112:115]
	v_mfma_f32_16x16x32_bf16 v[92:95], v[178:181], v[218:221], v[92:95]
	v_mfma_f32_16x16x32_bf16 v[84:87], v[190:193], v[218:221], v[84:87]
	v_mfma_f32_16x16x32_bf16 v[68:71], v[178:181], v[226:229], v[68:71]
	v_mfma_f32_16x16x32_bf16 v[64:67], v[190:193], v[226:229], v[64:67]
	s_setprio 1
	s_barrier
	s_add_i32 s17, s17, s30
	v_lshl_add_u64 v[230:231], v[88:89], 0, v[154:155]
	s_mov_b32 m0, s17
	ds_read_b128 v[198:201], v189 offset:16384
	ds_read_b128 v[202:205], v189 offset:17408
	ds_read_b128 v[206:209], v189 offset:18432
	ds_read_b128 v[210:213], v189 offset:19456
	ds_read_b128 v[214:217], v189 offset:20480
	ds_read_b128 v[218:221], v189 offset:21504
	ds_read_b128 v[222:225], v189 offset:22528
	ds_read_b128 v[226:229], v189 offset:23552
	global_load_lds_dwordx4 v[230:231], off
	v_lshl_add_u64 v[232:233], v[88:89], 0, v[164:165]
	s_add_i32 m0, s17, 0x2000
	v_lshl_add_u64 v[234:235], v[88:89], 0, s[80:81]
	s_add_i32 s17, s19, s30
	global_load_lds_dwordx4 v[232:233], off
	v_lshl_add_u64 v[236:237], v[234:235], 0, v[154:155]
	s_mov_b32 m0, s17
	v_lshl_add_u64 v[234:235], v[234:235], 0, v[164:165]
	global_load_lds_dwordx4 v[236:237], off
	s_add_i32 m0, s17, 0x2000
	v_lshl_add_u64 v[236:237], v[90:91], 0, v[162:163]
	global_load_lds_dwordx4 v[234:235], off
	v_lshl_add_u64 v[234:235], v[90:91], 0, v[160:161]
	s_mov_b32 m0, s35
	s_nop 0
	global_load_lds_dwordx4 v[234:235], off
	s_mov_b32 m0, s36
	s_nop 0
	global_load_lds_dwordx4 v[236:237], off
	s_waitcnt vmcnt(8)
	s_waitcnt lgkmcnt(0)
	s_barrier
; #define PG8_STAGE(bufoff, gbase, voff) do { _Pragma("unroll") for (int _i = 0; _i < 2; ++_i) \
;         __builtin_amdgcn_global_load_lds((const unsigned*)((const char*)(gbase) + (voff)[_i]), (PG8_LAS unsigned*)(lds + (bufoff) + ldsw + _i * 8192), 16, 0, 0); } while (0)
; #define PG8_LDA(dst, b, h) do { _Pragma("unroll") for (int m = 0; m < 4; ++m) _Pragma("unroll") for (int k = 0; k < 2; ++k) dst[m][k] = *(const PG8_LAS bf16x8*)(lds + PG8_SA(b, h) + aoff + m * 2048 + k * 1024); } while (0)
; #define PG8_LDB(dst, b, h) do { _Pragma("unroll") for (int n = 0; n < 2; ++n) _Pragma("unroll") for (int k = 0; k < 2; ++k) dst[n][k] = *(const PG8_LAS bf16x8*)(lds + PG8_SB(b, h) + boff + n * 2048 + k * 1024); } while (0)
; #define PG8_MMA(ai, bj, At, Bt) do { __builtin_amdgcn_s_setprio(1); _Pragma("unroll") for (int m = 0; m < 4; ++m) _Pragma("unroll") for (int n = 0; n < 2; ++n) _Pragma("unroll") for (int k = 0; k < 2; ++k) \
;         acc[ai][bj][m][n] = __builtin_amdgcn_mfma_f32_16x16x32_bf16(Bt[n][k], At[m][k], acc[ai][bj][m][n], 0, 0, 0); __builtin_amdgcn_s_setprio(0); } while (0)
; #define PG8_WAIT_V(n) asm volatile("s_waitcnt vmcnt(" #n ")" ::: "memory")
; #define PG8_WAIT_L(n) asm volatile("s_waitcnt lgkmcnt(" #n ")" ::: "memory")
; #define PG8_BAR __builtin_amdgcn_s_barrier()
; #define PG8_SCHED __builtin_amdgcn_sched_barrier(0)
; template <class Epi, class Sched, bool ALIGN_EPI = false, bool SP2 = false>
; __device__ __forceinline__ void gemm_phase(PG8_LAS unsigned char* lds, const Gemm g, const Sched& S, const Epi& E) {
;     ...
;             PG8_WAIT_V(8); PG8_WAIT_L(0); PG8_BAR; PG8_MMA(1, 0, At, B0); PG8_MMA(1, 1, At, B1); PG8_BAR; PG8_SCHED;
;             PG8_LDB(B0, 1, 0); PG8_LDB(B1, 1, 1); PG8_SCHED; PG8_LDA(At, 1, 0); PG8_STAGE(PG8_SA(0, 1), a2 + hstep, voffA);
;             PG8_WAIT_V(8); PG8_WAIT_L(0); PG8_BAR; PG8_MMA(0, 0, At, B0); PG8_MMA(0, 1, At, B1); PG8_BAR; PG8_SCHED;
	s_setprio 0
	s_waitcnt lgkmcnt(0)
	v_mfma_f32_16x16x32_bf16 v[60:63], v[96:99], v[198:201], v[60:63]
	v_mfma_f32_16x16x32_bf16 v[56:59], v[144:147], v[198:201], v[56:59]
	v_mfma_f32_16x16x32_bf16 v[44:47], v[96:99], v[206:209], v[44:47]
	v_mfma_f32_16x16x32_bf16 v[40:43], v[144:147], v[206:209], v[40:43]
	v_mfma_f32_16x16x32_bf16 v[28:31], v[96:99], v[214:217], v[28:31]
	v_mfma_f32_16x16x32_bf16 v[24:27], v[144:147], v[214:217], v[24:27]
	v_mfma_f32_16x16x32_bf16 v[12:15], v[96:99], v[222:225], v[12:15]
	v_mfma_f32_16x16x32_bf16 v[8:11], v[144:147], v[222:225], v[8:11]
	v_mfma_f32_16x16x32_bf16 v[60:63], v[100:103], v[202:205], v[60:63]
	v_mfma_f32_16x16x32_bf16 v[56:59], v[148:151], v[202:205], v[56:59]
	v_mfma_f32_16x16x32_bf16 v[44:47], v[100:103], v[210:213], v[44:47]
	v_mfma_f32_16x16x32_bf16 v[40:43], v[148:151], v[210:213], v[40:43]
	v_mfma_f32_16x16x32_bf16 v[28:31], v[100:103], v[218:221], v[28:31]
	v_mfma_f32_16x16x32_bf16 v[24:27], v[148:151], v[218:221], v[24:27]
	v_mfma_f32_16x16x32_bf16 v[12:15], v[100:103], v[226:229], v[12:15]
	v_mfma_f32_16x16x32_bf16 v[8:11], v[148:151], v[226:229], v[8:11]
	s_setprio 1
	s_setprio 0
	v_mfma_f32_16x16x32_bf16 v[52:55], v[174:177], v[198:201], v[52:55]
	v_mfma_f32_16x16x32_bf16 v[48:51], v[182:185], v[198:201], v[48:51]
	v_mfma_f32_16x16x32_bf16 v[36:39], v[174:177], v[206:209], v[36:39]
	v_mfma_f32_16x16x32_bf16 v[32:35], v[182:185], v[206:209], v[32:35]
	v_mfma_f32_16x16x32_bf16 v[20:23], v[174:177], v[214:217], v[20:23]
	v_mfma_f32_16x16x32_bf16 v[16:19], v[182:185], v[214:217], v[16:19]
	v_mfma_f32_16x16x32_bf16 v[4:7], v[174:177], v[222:225], v[4:7]
	v_mfma_f32_16x16x32_bf16 v[0:3], v[182:185], v[222:225], v[0:3]
	v_mfma_f32_16x16x32_bf16 v[52:55], v[178:181], v[202:205], v[52:55]
	v_mfma_f32_16x16x32_bf16 v[48:51], v[190:193], v[202:205], v[48:51]
	v_mfma_f32_16x16x32_bf16 v[36:39], v[178:181], v[210:213], v[36:39]
	v_mfma_f32_16x16x32_bf16 v[32:35], v[190:193], v[210:213], v[32:35]
	v_mfma_f32_16x16x32_bf16 v[20:23], v[178:181], v[218:221], v[20:23]
	v_mfma_f32_16x16x32_bf16 v[16:19], v[190:193], v[218:221], v[16:19]
	v_mfma_f32_16x16x32_bf16 v[4:7], v[178:181], v[226:229], v[4:7]
	v_mfma_f32_16x16x32_bf16 v[0:3], v[190:193], v[226:229], v[0:3]
	s_setprio 1
	s_barrier
	s_add_i32 s17, 0, 0x18000
	s_add_i32 s19, 0, 0x1c000
	v_add_u32_e32 v148, s17, v187
	v_add_u32_e32 v190, s19, v187
	ds_read_b128 v[96:99], v148
	ds_read_b128 v[100:103], v148 offset:1024
	ds_read_b128 v[144:147], v148 offset:2048
	ds_read_b128 v[148:151], v148 offset:3072
	ds_read_b128 v[174:177], v190
	ds_read_b128 v[178:181], v190 offset:1024
	ds_read_b128 v[182:185], v190 offset:2048
	ds_read_b128 v[190:193], v190 offset:3072
	v_lshl_add_u64 v[90:91], v[90:91], 0, s[80:81]
	s_mov_b32 m0, s37
	v_lshl_add_u64 v[238:239], v[90:91], 0, v[160:161]
	ds_read_b128 v[198:201], v189 offset:32768
	ds_read_b128 v[202:205], v189 offset:33792
	ds_read_b128 v[206:209], v189 offset:34816
	ds_read_b128 v[210:213], v189 offset:35840
	ds_read_b128 v[214:217], v189 offset:36864
	ds_read_b128 v[218:221], v189 offset:37888
	ds_read_b128 v[222:225], v189 offset:38912
	ds_read_b128 v[226:229], v189 offset:39936
	global_load_lds_dwordx4 v[238:239], off
	v_lshl_add_u64 v[90:91], v[90:91], 0, v[162:163]
	s_mov_b32 m0, s38
	s_nop 0
	global_load_lds_dwordx4 v[90:91], off
	s_waitcnt vmcnt(8)
	s_waitcnt lgkmcnt(0)
	s_barrier
	s_setprio 0
	s_waitcnt lgkmcnt(0)
	v_mfma_f32_16x16x32_bf16 v[140:143], v[96:99], v[198:201], v[140:143]
	v_mfma_f32_16x16x32_bf16 v[136:139], v[144:147], v[198:201], v[136:139]
	v_mfma_f32_16x16x32_bf16 v[124:127], v[96:99], v[206:209], v[124:127]
	v_mfma_f32_16x16x32_bf16 v[120:123], v[144:147], v[206:209], v[120:123]
	v_mfma_f32_16x16x32_bf16 v[108:111], v[96:99], v[214:217], v[108:111]
	v_mfma_f32_16x16x32_bf16 v[104:107], v[144:147], v[214:217], v[104:107]
	v_mfma_f32_16x16x32_bf16 v[76:79], v[96:99], v[222:225], v[76:79]
	v_mfma_f32_16x16x32_bf16 v[72:75], v[144:147], v[222:225], v[72:75]
	v_mfma_f32_16x16x32_bf16 v[140:143], v[100:103], v[202:205], v[140:143]
	v_mfma_f32_16x16x32_bf16 v[136:139], v[148:151], v[202:205], v[136:139]
	v_mfma_f32_16x16x32_bf16 v[124:127], v[100:103], v[210:213], v[124:127]
	v_mfma_f32_16x16x32_bf16 v[120:123], v[148:151], v[210:213], v[120:123]
	v_mfma_f32_16x16x32_bf16 v[108:111], v[100:103], v[218:221], v[108:111]
	v_mfma_f32_16x16x32_bf16 v[104:107], v[148:151], v[218:221], v[104:107]
	v_mfma_f32_16x16x32_bf16 v[76:79], v[100:103], v[226:229], v[76:79]
	v_mfma_f32_16x16x32_bf16 v[72:75], v[148:151], v[226:229], v[72:75]
	s_setprio 1
	s_setprio 0
	v_mfma_f32_16x16x32_bf16 v[132:135], v[174:177], v[198:201], v[132:135]
	v_mfma_f32_16x16x32_bf16 v[128:131], v[182:185], v[198:201], v[128:131]
	v_mfma_f32_16x16x32_bf16 v[116:119], v[174:177], v[206:209], v[116:119]
	v_mfma_f32_16x16x32_bf16 v[112:115], v[182:185], v[206:209], v[112:115]
	v_mfma_f32_16x16x32_bf16 v[90:93], v[174:177], v[214:217], v[92:95]
	v_mfma_f32_16x16x32_bf16 v[84:87], v[182:185], v[214:217], v[84:87]
	v_mfma_f32_16x16x32_bf16 v[68:71], v[174:177], v[222:225], v[68:71]
	v_mfma_f32_16x16x32_bf16 v[64:67], v[182:185], v[222:225], v[64:67]
	v_mfma_f32_16x16x32_bf16 v[132:135], v[178:181], v[202:205], v[132:135]
	v_mfma_f32_16x16x32_bf16 v[128:131], v[190:193], v[202:205], v[128:131]
	v_mfma_f32_16x16x32_bf16 v[116:119], v[178:181], v[210:213], v[116:119]
	v_mfma_f32_16x16x32_bf16 v[112:115], v[190:193], v[210:213], v[112:115]
	v_mfma_f32_16x16x32_bf16 v[92:95], v[178:181], v[218:221], v[90:93]
	v_mfma_f32_16x16x32_bf16 v[84:87], v[190:193], v[218:221], v[84:87]
	v_mfma_f32_16x16x32_bf16 v[68:71], v[178:181], v[226:229], v[68:71]
	v_mfma_f32_16x16x32_bf16 v[64:67], v[190:193], v[226:229], v[64:67]
	s_setprio 1
	s_barrier
; #define PG8_STAGE(bufoff, gbase, voff) do { _Pragma("unroll") for (int _i = 0; _i < 2; ++_i) \
;         __builtin_amdgcn_global_load_lds((const unsigned*)((const char*)(gbase) + (voff)[_i]), (PG8_LAS unsigned*)(lds + (bufoff) + ldsw + _i * 8192), 16, 0, 0); } while (0)
; #define PG8_LDA(dst, b, h) do { _Pragma("unroll") for (int m = 0; m < 4; ++m) _Pragma("unroll") for (int k = 0; k < 2; ++k) dst[m][k] = *(const PG8_LAS bf16x8*)(lds + PG8_SA(b, h) + aoff + m * 2048 + k * 1024); } while (0)
; #define PG8_MMA(ai, bj, At, Bt) do { __builtin_amdgcn_s_setprio(1); _Pragma("unroll") for (int m = 0; m < 4; ++m) _Pragma("unroll") for (int n = 0; n < 2; ++n) _Pragma("unroll") for (int k = 0; k < 2; ++k) \
;         acc[ai][bj][m][n] = __builtin_amdgcn_mfma_f32_16x16x32_bf16(Bt[n][k], At[m][k], acc[ai][bj][m][n], 0, 0, 0); __builtin_amdgcn_s_setprio(0); } while (0)
; #define PG8_WAIT_V(n) asm volatile("s_waitcnt vmcnt(" #n ")" ::: "memory")
; #define PG8_WAIT_L(n) asm volatile("s_waitcnt lgkmcnt(" #n ")" ::: "memory")
; #define PG8_BAR __builtin_amdgcn_s_barrier()
; #define PG8_SCHED __builtin_amdgcn_sched_barrier(0)
; template <class Epi, class Sched, bool ALIGN_EPI = false, bool SP2 = false>
; __device__ __forceinline__ void gemm_phase(PG8_LAS unsigned char* lds, const Gemm g, const Sched& S, const Epi& E) {
;     ...
;         for (int t = 0; t < nt; t += 2) {
;             const bool last = (t == nt - 2);
;             const char* a1 = cA + (size_t)(t + 1) * kstep;
;             const char* a2 = last ? nA : cA + (size_t)(t + 2) * kstep; const char* b2 = last ? nB : cB + (size_t)(t + 2) * kstep;
;             const char* a3 = a2 + (last ? knext : kstep); const char* b3 = b2 + (last ? knext : kstep);
;     ...
;             PG8_LDA(At, 1, 1); PG8_STAGE(PG8_SB(1, 0), b3, voffB); PG8_STAGE(PG8_SB(1, 1), b3 + hstep, voffB); PG8_STAGE(PG8_SA(1, 0), a3, voffA);
;             PG8_WAIT_V(8); PG8_WAIT_L(0); PG8_BAR; PG8_MMA(1, 0, At, B0); PG8_MMA(1, 1, At, B1); PG8_BAR; PG8_SCHED;
	s_add_i32 s17, s17, s30
	v_lshl_add_u64 v[90:91], v[230:231], 0, s[84:85]
	s_mov_b32 m0, s17
	ds_read_b128 v[198:201], v189 offset:49152
	ds_read_b128 v[202:205], v189 offset:50176
	ds_read_b128 v[206:209], v189 offset:51200
	ds_read_b128 v[210:213], v189 offset:52224
	ds_read_b128 v[214:217], v189 offset:53248
	ds_read_b128 v[218:221], v189 offset:54272
	ds_read_b128 v[222:225], v189 offset:55296
	ds_read_b128 v[226:229], v189 offset:56320
	global_load_lds_dwordx4 v[90:91], off
	v_lshl_add_u64 v[90:91], v[232:233], 0, s[84:85]
	s_add_i32 m0, s17, 0x2000
	v_lshl_add_u64 v[88:89], v[88:89], 0, s[86:87]
	s_add_i32 s17, s19, s30
	global_load_lds_dwordx4 v[90:91], off
	v_lshl_add_u64 v[90:91], v[88:89], 0, v[154:155]
	s_mov_b32 m0, s17
	v_lshl_add_u64 v[88:89], v[88:89], 0, v[164:165]
	global_load_lds_dwordx4 v[90:91], off
	s_add_i32 m0, s17, 0x2000
	s_nop 0
	global_load_lds_dwordx4 v[88:89], off
	v_lshl_add_u64 v[88:89], v[234:235], 0, s[84:85]
	s_mov_b32 m0, s41
	s_nop 0
	global_load_lds_dwordx4 v[88:89], off
	v_lshl_add_u64 v[88:89], v[236:237], 0, s[84:85]
	s_mov_b32 m0, s42
	s_nop 0
	global_load_lds_dwordx4 v[88:89], off
	s_waitcnt vmcnt(8)
	s_waitcnt lgkmcnt(0)
	s_barrier
	s_setprio 0
	s_waitcnt lgkmcnt(0)
	v_mfma_f32_16x16x32_bf16 v[60:63], v[96:99], v[198:201], v[60:63]
	v_mfma_f32_16x16x32_bf16 v[56:59], v[144:147], v[198:201], v[56:59]
	v_mfma_f32_16x16x32_bf16 v[44:47], v[96:99], v[206:209], v[44:47]
	v_mfma_f32_16x16x32_bf16 v[40:43], v[144:147], v[206:209], v[40:43]
	v_mfma_f32_16x16x32_bf16 v[28:31], v[96:99], v[214:217], v[28:31]
	v_mfma_f32_16x16x32_bf16 v[24:27], v[144:147], v[214:217], v[24:27]
	v_mfma_f32_16x16x32_bf16 v[12:15], v[96:99], v[222:225], v[12:15]
	v_mfma_f32_16x16x32_bf16 v[8:11], v[144:147], v[222:225], v[8:11]
	v_mfma_f32_16x16x32_bf16 v[60:63], v[100:103], v[202:205], v[60:63]
	v_mfma_f32_16x16x32_bf16 v[56:59], v[148:151], v[202:205], v[56:59]
	v_mfma_f32_16x16x32_bf16 v[44:47], v[100:103], v[210:213], v[44:47]
	v_mfma_f32_16x16x32_bf16 v[40:43], v[148:151], v[210:213], v[40:43]
	v_mfma_f32_16x16x32_bf16 v[28:31], v[100:103], v[218:221], v[28:31]
	v_mfma_f32_16x16x32_bf16 v[24:27], v[148:151], v[218:221], v[24:27]
	v_mfma_f32_16x16x32_bf16 v[12:15], v[100:103], v[226:229], v[12:15]
	v_mfma_f32_16x16x32_bf16 v[8:11], v[148:151], v[226:229], v[8:11]
	s_setprio 1
	s_setprio 0
	v_mfma_f32_16x16x32_bf16 v[52:55], v[174:177], v[198:201], v[52:55]
	v_mfma_f32_16x16x32_bf16 v[48:51], v[182:185], v[198:201], v[48:51]
	v_mfma_f32_16x16x32_bf16 v[36:39], v[174:177], v[206:209], v[36:39]
	v_mfma_f32_16x16x32_bf16 v[32:35], v[182:185], v[206:209], v[32:35]
	v_mfma_f32_16x16x32_bf16 v[20:23], v[174:177], v[214:217], v[20:23]
	v_mfma_f32_16x16x32_bf16 v[16:19], v[182:185], v[214:217], v[16:19]
	v_mfma_f32_16x16x32_bf16 v[4:7], v[174:177], v[222:225], v[4:7]
	v_mfma_f32_16x16x32_bf16 v[0:3], v[182:185], v[222:225], v[0:3]
	v_mfma_f32_16x16x32_bf16 v[52:55], v[178:181], v[202:205], v[52:55]
	v_mfma_f32_16x16x32_bf16 v[48:51], v[190:193], v[202:205], v[48:51]
	v_mfma_f32_16x16x32_bf16 v[36:39], v[178:181], v[210:213], v[36:39]
	v_mfma_f32_16x16x32_bf16 v[32:35], v[190:193], v[210:213], v[32:35]
	v_mfma_f32_16x16x32_bf16 v[20:23], v[178:181], v[218:221], v[20:23]
	v_mfma_f32_16x16x32_bf16 v[16:19], v[190:193], v[218:221], v[16:19]
	v_mfma_f32_16x16x32_bf16 v[4:7], v[178:181], v[226:229], v[4:7]
	v_mfma_f32_16x16x32_bf16 v[0:3], v[190:193], v[226:229], v[0:3]
	s_setprio 1
	s_barrier
	v_lshl_add_u64 v[80:81], v[80:81], 0, s[88:89]
	s_cmp_ge_i32 s11, s1
	v_lshl_add_u64 v[82:83], v[82:83], 0, s[88:89]
	s_cbranch_scc1 .LBB0_914
